# merge: task index remapped so each XCD owns 16 row-tiles x all 8 column-tiles (X tiles shared through that XCD's L2 by the 8 concurrent column tiles)
# speedup vs baseline: 1.0046x; 1.0045x over previous
; DI f32x16 mfma(bf16x8 a, bf16x8 b, f32x16 c) { return __builtin_amdgcn_mfma_f32_32x32x16_bf16(a, b, c, 0, 0, 0); }
; DI f32x16 zero16() { f32x16 z; for (int i = 0; i < 16; ++i) z[i] = 0.f; return z; }
; DI int tidx() { int t = threadIdx.x; asm volatile("" : "+v"(t)); return t; }
; template <bool RFA, bool RFB, class LA, class LB, class EPI>
; DI void gemm_tile2s(u16* smem, int nk, LA la, LB lb, EPI epi) {
;   const int tid = tidx(), lane = tid & 63, wave = tid >> 6;
;   const int wm = wave >> 2, wn = wave & 3, lr = lane & 31, lh = lane >> 5;
;   u16* As = smem;
;   u16* Bs = smem + 2 * TILE_ELEMS;
;   f32x16 acc[2];
;   acc[0] = zero16(); acc[1] = zero16();
;   u32x4 ra0[2], rb0[2], ra1[2], rb1[2];
;   auto ld = [&](u32x4 (&ra)[2], u32x4 (&rb)[2], int kt) __attribute__((always_inline)) {
;     const int k0 = kt * 64;
; #pragma unroll
;     for (int i = 0; i < 2; ++i) { const int c = tid + NTH * i; ra[i] = la(A_ROW(c), k0 + A_KC(c) * 8); rb[i] = lb(B_ROW(c), k0 + B_KC(c) * 8); }
;   };
;   auto stl = [&](u32x4 (&ra)[2], u32x4 (&rb)[2], int buf) __attribute__((always_inline)) {
; #pragma unroll
;     for (int i = 0; i < 2; ++i) {
;       const int c = tid + NTH * i;
;       *(u32x4*)(As + buf * TILE_ELEMS + A_ROW(c) * LDT + A_KC(c) * 8) = ra[i];
;       *(u32x4*)(Bs + buf * TILE_ELEMS + B_ROW(c) * LDT + B_KC(c) * 8) = rb[i];
;     }
;   };
;   auto compute = [&](int buf) __attribute__((always_inline)) {
;     const u16* Ab = As + buf * TILE_ELEMS + (wm * 64 + lr) * LDT + lh * 8;
;     const u16* Bb = Bs + buf * TILE_ELEMS + (wn * 32 + lr) * LDT + lh * 8;
; #pragma unroll
;     for (int ks = 0; ks < 4; ++ks) {
;       const bf16x8 a0 = *(const bf16x8*)(Ab + ks * 16);
;       const bf16x8 a1 = *(const bf16x8*)(Ab + 32 * LDT + ks * 16);
;       const bf16x8 b = *(const bf16x8*)(Bb + ks * 16);
;       acc[0] = mfma(a0, b, acc[0]);
;       acc[1] = mfma(a1, b, acc[1]);
;     }
;   };
;   ld(ra0, rb0, 0);
;   if (nk > 1) ld(ra1, rb1, 1);
;   stl(ra0, rb0, 0);
;   if (nk > 2) ld(ra0, rb0, 2);
;   __syncthreads();
; DI void phase_merge(const Prm& p, u16* smem, int l, int& base) {
;   TASK_LOOP(t, 8 * 128, base) {
;     const int tn = t & 7, tm = t >> 3, n0 = tn * 128, m0 = tm * 128;
;     f32x16 macc[2];
;     macc[0] = zero16(); macc[1] = zero16();
;     merge_branch(p, smem, p.PaT + (size_t)l * 1024 * 768, p.UT, 768, 0, n0, m0, macc);
.LBB0_2250:
	v_readlane_b32 s36, v253, 28
	v_readlane_b32 s37, v253, 29
	v_readlane_b32 s38, v253, 30
	v_readlane_b32 s39, v253, 31
	v_readlane_b32 s40, v252, 4
	v_readlane_b32 s41, v252, 5
	v_readlane_b32 s42, v252, 6
	v_readlane_b32 s43, v252, 7
	v_readlane_b32 s48, v253, 20
	v_readlane_b32 s49, v253, 21
	v_and_b32_e32 v226, 7, v224
	v_lshlrev_b32_e32 v226, 4, v226
	v_lshrrev_b32_e32 v227, 3, v224
	v_and_b32_e32 v228, 0xffffffe3, v227
	v_lshrrev_b32_e32 v229, 1, v227
	v_and_b32_e32 v229, 12, v229
	v_or_b32_e32 v228, v228, v229
	v_lshlrev_b32_e32 v229, 2, v227
	v_and_b32_e32 v229, 16, v229
	v_or_b32_e32 v228, v228, v229
	s_movk_i32 s52, 0x600
	v_mad_u32_u24 v210, v228, s52, v226
	v_mad_u32_u24 v214, v227, s52, v226
	s_movk_i32 s52, 0x100
	v_mad_u32_u24 v211, v228, s52, v226
	v_mad_u32_u24 v215, v227, s52, v226
	s_movk_i32 s52, 0x300
	v_mad_u32_u24 v212, v228, s52, v226
	v_mad_u32_u24 v216, v227, s52, v226
	s_movk_i32 s52, 0x200
	v_mad_u32_u24 v213, v228, s52, v226
	v_mad_u32_u24 v217, v227, s52, v226
	s_movk_i32 s52, 0x90
	v_mad_u32_u24 v218, v227, s52, v226
	v_lshrrev_b32_e32 v226, 1, v224
	v_and_b32_e32 v227, 16, v226
	v_and_b32_e32 v228, 31, v224
	v_lshrrev_b32_e32 v229, 2, v224
	v_and_b32_e32 v229, 64, v229
	v_and_b32_e32 v226, 0x60, v226
	v_or_b32_e32 v226, v226, v228
	v_or_b32_e32 v228, v229, v228
	v_mad_u32_u24 v219, v228, s52, v227
	v_mad_u32_u24 v220, v226, s52, v227
	v_add_u32_e32 v220, 0xd800, v220
	v_add_u32_e32 v223, 0xd800, v218
	v_or_b32_e32 v229, v229, v227
	v_lshlrev_b32_e32 v229, 1, v229
	v_lshl_add_u32 v221, v226, 13, v229
	v_lshl_add_u32 v222, v226, 11, v229
	s_and_b32 s52, s31, 7
	s_lshl_b32 s52, s52, 7
	s_lshr_b32 s53, s31, 8
	s_lshl_b32 s53, s53, 5
	s_or_b32 s52, s52, s53
	s_bfe_u32 s53, s31, 0x50003
	s_or_b32 s52, s52, s53
	s_and_b32 s58, s52, 7
	s_lshl_b32 s58, s58, 7
	s_lshr_b32 s59, s52, 3
	s_lshl_b32 s59, s59, 7
	s_mul_i32 s52, s58, 0x600
	s_add_u32 s0, s16, s52
	s_addc_u32 s1, s17, 0
	s_add_u32 s2, s0, 0x18000
	s_addc_u32 s3, s1, 0
	s_mul_i32 s52, s59, 0x600
	s_add_u32 s4, s14, s52
	s_addc_u32 s5, s15, 0
	s_add_u32 s6, s4, 0x18000
	s_addc_u32 s7, s5, 0
	global_load_dwordx4 v[66:69], v210, s[0:1]
	global_load_dwordx4 v[70:73], v210, s[2:3]
	global_load_dwordx4 v[74:77], v214, s[4:5]
	global_load_dwordx4 v[78:81], v214, s[6:7]
	global_load_dwordx4 v[82:85], v210, s[0:1] offset:128
	global_load_dwordx4 v[86:89], v210, s[2:3] offset:128
	global_load_dwordx4 v[90:93], v214, s[4:5] offset:128
	global_load_dwordx4 v[94:97], v214, s[6:7] offset:128
	global_load_dwordx4 v[98:101], v210, s[0:1] offset:256
	global_load_dwordx4 v[102:105], v210, s[2:3] offset:256
	global_load_dwordx4 v[106:109], v214, s[4:5] offset:256
	global_load_dwordx4 v[110:113], v214, s[6:7] offset:256
	global_load_dwordx4 v[114:117], v210, s[0:1] offset:384
	global_load_dwordx4 v[118:121], v210, s[2:3] offset:384
	global_load_dwordx4 v[122:125], v214, s[4:5] offset:384
	global_load_dwordx4 v[126:129], v214, s[6:7] offset:384
	s_waitcnt vmcnt(8)
	ds_write_b128 v218, v[66:69]
	ds_write_b128 v218, v[70:73] offset:9216
	ds_write_b128 v223, v[74:77]
	ds_write_b128 v223, v[78:81] offset:9216
	ds_write_b128 v218, v[82:85] offset:18432
	ds_write_b128 v218, v[86:89] offset:27648
	ds_write_b128 v223, v[90:93] offset:18432
	ds_write_b128 v223, v[94:97] offset:27648
	global_load_dwordx4 v[66:69], v210, s[0:1] offset:512
	global_load_dwordx4 v[70:73], v210, s[2:3] offset:512
	global_load_dwordx4 v[74:77], v214, s[4:5] offset:512
	global_load_dwordx4 v[78:81], v214, s[6:7] offset:512
	global_load_dwordx4 v[82:85], v210, s[0:1] offset:640
	global_load_dwordx4 v[86:89], v210, s[2:3] offset:640
	global_load_dwordx4 v[90:93], v214, s[4:5] offset:640
	global_load_dwordx4 v[94:97], v214, s[6:7] offset:640
	s_waitcnt vmcnt(0)
	s_waitcnt lgkmcnt(0)
	s_barrier
	ds_read_b128 v[130:133], v219
	ds_read_b128 v[134:137], v220
	ds_read_b128 v[138:141], v219 offset:4608
	ds_read_b128 v[142:145], v219 offset:32
	ds_read_b128 v[146:149], v220 offset:32
	ds_read_b128 v[150:153], v219 offset:4640
	s_waitcnt lgkmcnt(0)
.Lmrg_task:
	s_lshl_b32 s52, s59, 13
	s_lshl_b32 s53, s58, 1
	s_add_u32 s52, s52, s53
	s_add_u32 s8, s42, s52
	s_addc_u32 s9, s43, 0
	s_add_u32 s10, s8, 0x1000
	s_addc_u32 s11, s9, 0
	s_lshl_b32 s52, s59, 11
	s_add_u32 s52, s52, s53
	s_add_u32 s12, s48, s52
	s_addc_u32 s13, s49, 0
	ds_read_b128 v[154:157], v219 offset:64
	ds_read_b128 v[158:161], v220 offset:64
	ds_read_b128 v[162:165], v219 offset:4672
	v_mfma_f32_32x32x16_bf16 v[18:33], v[130:133], v[134:137], 0
	ds_read_b128 v[166:169], v219 offset:96
	ds_read_b128 v[170:173], v220 offset:96
	ds_read_b128 v[174:177], v219 offset:4704
	v_mfma_f32_32x32x16_bf16 v[2:17], v[138:141], v[134:137], 0
	s_waitcnt vmcnt(16)
	ds_write_b128 v218, v[98:101] offset:36864
	ds_write_b128 v218, v[102:105] offset:46080
	v_mfma_f32_32x32x16_bf16 v[18:33], v[142:145], v[146:149], v[18:33]
	ds_write_b128 v223, v[106:109] offset:36864
	ds_write_b128 v223, v[110:113] offset:46080
	v_mfma_f32_32x32x16_bf16 v[2:17], v[150:153], v[146:149], v[2:17]
	global_load_dwordx4 v[98:101], v210, s[0:1] offset:768
	global_load_dwordx4 v[102:105], v210, s[2:3] offset:768
	global_load_dwordx4 v[106:109], v214, s[4:5] offset:768
	global_load_dwordx4 v[110:113], v214, s[6:7] offset:768
	ds_read_b128 v[130:133], v219 offset:18432
	ds_read_b128 v[134:137], v220 offset:18432
	ds_read_b128 v[138:141], v219 offset:23040
	s_waitcnt lgkmcnt(11)
	v_mfma_f32_32x32x16_bf16 v[18:33], v[154:157], v[158:161], v[18:33]
	ds_read_b128 v[142:145], v219 offset:18464
	ds_read_b128 v[146:149], v220 offset:18464
	ds_read_b128 v[150:153], v219 offset:23072
	s_waitcnt lgkmcnt(13)
	v_mfma_f32_32x32x16_bf16 v[2:17], v[162:165], v[158:161], v[2:17]
	s_waitcnt lgkmcnt(11)
	v_mfma_f32_32x32x16_bf16 v[18:33], v[166:169], v[170:173], v[18:33]
	s_waitcnt lgkmcnt(10)
	v_mfma_f32_32x32x16_bf16 v[2:17], v[174:177], v[170:173], v[2:17]
	s_waitcnt lgkmcnt(0)
	s_barrier
; DI f32x16 mfma(bf16x8 a, bf16x8 b, f32x16 c) { return __builtin_amdgcn_mfma_f32_32x32x16_bf16(a, b, c, 0, 0, 0); }
; template <bool RFA, bool RFB, class LA, class LB, class EPI>
; DI void gemm_tile2s(u16* smem, int nk, LA la, LB lb, EPI epi) {
;     ...
;   auto ld = [&](u32x4 (&ra)[2], u32x4 (&rb)[2], int kt) __attribute__((always_inline)) {
;     const int k0 = kt * 64;
; #pragma unroll
;     for (int i = 0; i < 2; ++i) { const int c = tid + NTH * i; ra[i] = la(A_ROW(c), k0 + A_KC(c) * 8); rb[i] = lb(B_ROW(c), k0 + B_KC(c) * 8); }
;   };
;   auto stl = [&](u32x4 (&ra)[2], u32x4 (&rb)[2], int buf) __attribute__((always_inline)) {
; #pragma unroll
;     for (int i = 0; i < 2; ++i) {
;       const int c = tid + NTH * i;
;       *(u32x4*)(As + buf * TILE_ELEMS + A_ROW(c) * LDT + A_KC(c) * 8) = ra[i];
;       *(u32x4*)(Bs + buf * TILE_ELEMS + B_ROW(c) * LDT + B_KC(c) * 8) = rb[i];
;     }
;   };
;   auto compute = [&](int buf) __attribute__((always_inline)) {
;     const u16* Ab = As + buf * TILE_ELEMS + (wm * 64 + lr) * LDT + lh * 8;
;     const u16* Bb = Bs + buf * TILE_ELEMS + (wn * 32 + lr) * LDT + lh * 8;
; #pragma unroll
;     for (int ks = 0; ks < 4; ++ks) {
;       const bf16x8 a0 = *(const bf16x8*)(Ab + ks * 16);
;       const bf16x8 a1 = *(const bf16x8*)(Ab + 32 * LDT + ks * 16);
;       const bf16x8 b = *(const bf16x8*)(Bb + ks * 16);
;       acc[0] = mfma(a0, b, acc[0]);
;       acc[1] = mfma(a1, b, acc[1]);
;     }
;   };
;   ld(ra0, rb0, 0);
;   if (nk > 1) ld(ra1, rb1, 1);
;   stl(ra0, rb0, 0);
;   if (nk > 2) ld(ra0, rb0, 2);
;   __syncthreads();
; #pragma unroll 1
;   for (int kt = 0; kt < nk; kt += 2) {
;     compute(0);
;     if (kt + 1 < nk) { stl(ra1, rb1, 1); if (kt + 3 < nk) ld(ra1, rb1, kt + 3); }
;     __syncthreads();
;     if (kt + 1 < nk) {
;       compute(1);
;       if (kt + 2 < nk) { stl(ra0, rb0, 0); if (kt + 4 < nk) ld(ra0, rb0, kt + 4); }
;       __syncthreads();
	ds_read_b128 v[154:157], v219 offset:18496
	ds_read_b128 v[158:161], v220 offset:18496
	ds_read_b128 v[162:165], v219 offset:23104
	v_mfma_f32_32x32x16_bf16 v[18:33], v[130:133], v[134:137], v[18:33]
	ds_read_b128 v[166:169], v219 offset:18528
	ds_read_b128 v[170:173], v220 offset:18528
	ds_read_b128 v[174:177], v219 offset:23136
	v_mfma_f32_32x32x16_bf16 v[2:17], v[138:141], v[134:137], v[2:17]
	s_waitcnt vmcnt(16)
	ds_write_b128 v218, v[114:117]
	ds_write_b128 v218, v[118:121] offset:9216
	v_mfma_f32_32x32x16_bf16 v[18:33], v[142:145], v[146:149], v[18:33]
	ds_write_b128 v223, v[122:125]
	ds_write_b128 v223, v[126:129] offset:9216
	v_mfma_f32_32x32x16_bf16 v[2:17], v[150:153], v[146:149], v[2:17]
	global_load_dwordx4 v[114:117], v210, s[0:1] offset:896
	global_load_dwordx4 v[118:121], v210, s[2:3] offset:896
	global_load_dwordx4 v[122:125], v214, s[4:5] offset:896
	global_load_dwordx4 v[126:129], v214, s[6:7] offset:896
	ds_read_b128 v[130:133], v219 offset:36864
	ds_read_b128 v[134:137], v220 offset:36864
	ds_read_b128 v[138:141], v219 offset:41472
	s_waitcnt lgkmcnt(11)
	v_mfma_f32_32x32x16_bf16 v[18:33], v[154:157], v[158:161], v[18:33]
	ds_read_b128 v[142:145], v219 offset:36896
	ds_read_b128 v[146:149], v220 offset:36896
	ds_read_b128 v[150:153], v219 offset:41504
	s_waitcnt lgkmcnt(13)
	v_mfma_f32_32x32x16_bf16 v[2:17], v[162:165], v[158:161], v[2:17]
	s_waitcnt lgkmcnt(11)
	v_mfma_f32_32x32x16_bf16 v[18:33], v[166:169], v[170:173], v[18:33]
	s_waitcnt lgkmcnt(10)
	v_mfma_f32_32x32x16_bf16 v[2:17], v[174:177], v[170:173], v[2:17]
	s_waitcnt lgkmcnt(0)
	s_barrier
	ds_read_b128 v[154:157], v219 offset:36928
	ds_read_b128 v[158:161], v220 offset:36928
	ds_read_b128 v[162:165], v219 offset:41536
	v_mfma_f32_32x32x16_bf16 v[18:33], v[130:133], v[134:137], v[18:33]
	ds_read_b128 v[166:169], v219 offset:36960
	ds_read_b128 v[170:173], v220 offset:36960
	ds_read_b128 v[174:177], v219 offset:41568
	v_mfma_f32_32x32x16_bf16 v[2:17], v[138:141], v[134:137], v[2:17]
	s_waitcnt vmcnt(16)
	ds_write_b128 v218, v[66:69] offset:18432
	ds_write_b128 v218, v[70:73] offset:27648
	v_mfma_f32_32x32x16_bf16 v[18:33], v[142:145], v[146:149], v[18:33]
	ds_write_b128 v223, v[74:77] offset:18432
	ds_write_b128 v223, v[78:81] offset:27648
	v_mfma_f32_32x32x16_bf16 v[2:17], v[150:153], v[146:149], v[2:17]
	global_load_dwordx4 v[66:69], v210, s[0:1] offset:1024
	global_load_dwordx4 v[70:73], v210, s[2:3] offset:1024
	global_load_dwordx4 v[74:77], v214, s[4:5] offset:1024
	global_load_dwordx4 v[78:81], v214, s[6:7] offset:1024
	ds_read_b128 v[130:133], v219
	ds_read_b128 v[134:137], v220
	ds_read_b128 v[138:141], v219 offset:4608
	s_waitcnt lgkmcnt(11)
	v_mfma_f32_32x32x16_bf16 v[18:33], v[154:157], v[158:161], v[18:33]
	ds_read_b128 v[142:145], v219 offset:32
	ds_read_b128 v[146:149], v220 offset:32
	ds_read_b128 v[150:153], v219 offset:4640
	s_waitcnt lgkmcnt(13)
	v_mfma_f32_32x32x16_bf16 v[2:17], v[162:165], v[158:161], v[2:17]
	s_waitcnt lgkmcnt(11)
	v_mfma_f32_32x32x16_bf16 v[18:33], v[166:169], v[170:173], v[18:33]
	s_waitcnt lgkmcnt(10)
	v_mfma_f32_32x32x16_bf16 v[2:17], v[174:177], v[170:173], v[2:17]
	s_waitcnt lgkmcnt(0)
	s_barrier
	ds_read_b128 v[154:157], v219 offset:64
	ds_read_b128 v[158:161], v220 offset:64
	ds_read_b128 v[162:165], v219 offset:4672
	v_mfma_f32_32x32x16_bf16 v[18:33], v[130:133], v[134:137], v[18:33]
	ds_read_b128 v[166:169], v219 offset:96
	ds_read_b128 v[170:173], v220 offset:96
	ds_read_b128 v[174:177], v219 offset:4704
	v_mfma_f32_32x32x16_bf16 v[2:17], v[138:141], v[134:137], v[2:17]
	s_waitcnt vmcnt(16)
	ds_write_b128 v218, v[82:85] offset:36864
	ds_write_b128 v218, v[86:89] offset:46080
	v_mfma_f32_32x32x16_bf16 v[18:33], v[142:145], v[146:149], v[18:33]
	ds_write_b128 v223, v[90:93] offset:36864
	ds_write_b128 v223, v[94:97] offset:46080
	v_mfma_f32_32x32x16_bf16 v[2:17], v[150:153], v[146:149], v[2:17]
	global_load_dwordx4 v[82:85], v210, s[0:1] offset:1152
	global_load_dwordx4 v[86:89], v210, s[2:3] offset:1152
	global_load_dwordx4 v[90:93], v214, s[4:5] offset:1152
	global_load_dwordx4 v[94:97], v214, s[6:7] offset:1152
	ds_read_b128 v[130:133], v219 offset:18432
	ds_read_b128 v[134:137], v220 offset:18432
	ds_read_b128 v[138:141], v219 offset:23040
	s_waitcnt lgkmcnt(11)
	v_mfma_f32_32x32x16_bf16 v[18:33], v[154:157], v[158:161], v[18:33]
	ds_read_b128 v[142:145], v219 offset:18464
	ds_read_b128 v[146:149], v220 offset:18464
	ds_read_b128 v[150:153], v219 offset:23072
	s_waitcnt lgkmcnt(13)
	v_mfma_f32_32x32x16_bf16 v[2:17], v[162:165], v[158:161], v[2:17]
	s_waitcnt lgkmcnt(11)
	v_mfma_f32_32x32x16_bf16 v[18:33], v[166:169], v[170:173], v[18:33]
	s_waitcnt lgkmcnt(10)
	v_mfma_f32_32x32x16_bf16 v[2:17], v[174:177], v[170:173], v[2:17]
	s_waitcnt lgkmcnt(0)
	s_barrier
	ds_read_b128 v[154:157], v219 offset:18496
	ds_read_b128 v[158:161], v220 offset:18496
	ds_read_b128 v[162:165], v219 offset:23104
	v_mfma_f32_32x32x16_bf16 v[18:33], v[130:133], v[134:137], v[18:33]
	ds_read_b128 v[166:169], v219 offset:18528
	ds_read_b128 v[170:173], v220 offset:18528
	ds_read_b128 v[174:177], v219 offset:23136
	v_mfma_f32_32x32x16_bf16 v[2:17], v[138:141], v[134:137], v[2:17]
	s_waitcnt vmcnt(12)
	ds_write_b128 v218, v[98:101]
	ds_write_b128 v218, v[102:105] offset:9216
	v_mfma_f32_32x32x16_bf16 v[18:33], v[142:145], v[146:149], v[18:33]
	ds_write_b128 v223, v[106:109]
	ds_write_b128 v223, v[110:113] offset:9216
	v_mfma_f32_32x32x16_bf16 v[2:17], v[150:153], v[146:149], v[2:17]
	global_load_dwordx4 v[98:101], v210, s[0:1] offset:1280
	global_load_dwordx4 v[102:105], v210, s[2:3] offset:1280
	global_load_dwordx4 v[106:109], v214, s[4:5] offset:1280
	global_load_dwordx4 v[110:113], v214, s[6:7] offset:1280
	ds_read_b128 v[130:133], v219 offset:36864
	ds_read_b128 v[134:137], v220 offset:36864
	ds_read_b128 v[138:141], v219 offset:41472
	s_waitcnt lgkmcnt(11)
	v_mfma_f32_32x32x16_bf16 v[18:33], v[154:157], v[158:161], v[18:33]
	ds_read_b128 v[142:145], v219 offset:36896
	ds_read_b128 v[146:149], v220 offset:36896
	ds_read_b128 v[150:153], v219 offset:41504
	s_waitcnt lgkmcnt(13)
	v_mfma_f32_32x32x16_bf16 v[2:17], v[162:165], v[158:161], v[2:17]
	s_waitcnt lgkmcnt(11)
	v_mfma_f32_32x32x16_bf16 v[18:33], v[166:169], v[170:173], v[18:33]
	s_waitcnt lgkmcnt(10)
	v_mfma_f32_32x32x16_bf16 v[2:17], v[174:177], v[170:173], v[2:17]
	s_waitcnt lgkmcnt(0)
	s_barrier
; DI f32x16 mfma(bf16x8 a, bf16x8 b, f32x16 c) { return __builtin_amdgcn_mfma_f32_32x32x16_bf16(a, b, c, 0, 0, 0); }
; template <bool RFA, bool RFB, class LA, class LB, class EPI>
; DI void gemm_tile2s(u16* smem, int nk, LA la, LB lb, EPI epi) {
;     ...
;   auto ld = [&](u32x4 (&ra)[2], u32x4 (&rb)[2], int kt) __attribute__((always_inline)) {
;     const int k0 = kt * 64;
; #pragma unroll
;     for (int i = 0; i < 2; ++i) { const int c = tid + NTH * i; ra[i] = la(A_ROW(c), k0 + A_KC(c) * 8); rb[i] = lb(B_ROW(c), k0 + B_KC(c) * 8); }
;   };
;   auto stl = [&](u32x4 (&ra)[2], u32x4 (&rb)[2], int buf) __attribute__((always_inline)) {
; #pragma unroll
;     for (int i = 0; i < 2; ++i) {
;       const int c = tid + NTH * i;
;       *(u32x4*)(As + buf * TILE_ELEMS + A_ROW(c) * LDT + A_KC(c) * 8) = ra[i];
;       *(u32x4*)(Bs + buf * TILE_ELEMS + B_ROW(c) * LDT + B_KC(c) * 8) = rb[i];
;     }
;   };
;   auto compute = [&](int buf) __attribute__((always_inline)) {
;     const u16* Ab = As + buf * TILE_ELEMS + (wm * 64 + lr) * LDT + lh * 8;
;     const u16* Bb = Bs + buf * TILE_ELEMS + (wn * 32 + lr) * LDT + lh * 8;
; #pragma unroll
;     for (int ks = 0; ks < 4; ++ks) {
;       const bf16x8 a0 = *(const bf16x8*)(Ab + ks * 16);
;       const bf16x8 a1 = *(const bf16x8*)(Ab + 32 * LDT + ks * 16);
;       const bf16x8 b = *(const bf16x8*)(Bb + ks * 16);
;       acc[0] = mfma(a0, b, acc[0]);
;       acc[1] = mfma(a1, b, acc[1]);
;     }
;   };
;   ld(ra0, rb0, 0);
;   if (nk > 1) ld(ra1, rb1, 1);
;   stl(ra0, rb0, 0);
;   if (nk > 2) ld(ra0, rb0, 2);
;   __syncthreads();
; #pragma unroll 1
;   for (int kt = 0; kt < nk; kt += 2) {
;     compute(0);
;     if (kt + 1 < nk) { stl(ra1, rb1, 1); if (kt + 3 < nk) ld(ra1, rb1, kt + 3); }
;     __syncthreads();
;     if (kt + 1 < nk) {
;       compute(1);
;       if (kt + 2 < nk) { stl(ra0, rb0, 0); if (kt + 4 < nk) ld(ra0, rb0, kt + 4); }
;       __syncthreads();
	ds_read_b128 v[154:157], v219 offset:36928
	ds_read_b128 v[158:161], v220 offset:36928
	ds_read_b128 v[162:165], v219 offset:41536
	v_mfma_f32_32x32x16_bf16 v[18:33], v[130:133], v[134:137], v[18:33]
	ds_read_b128 v[166:169], v219 offset:36960
	ds_read_b128 v[170:173], v220 offset:36960
	ds_read_b128 v[174:177], v219 offset:41568
	v_mfma_f32_32x32x16_bf16 v[2:17], v[138:141], v[134:137], v[2:17]
	s_waitcnt vmcnt(12)
	ds_write_b128 v218, v[114:117] offset:18432
	ds_write_b128 v218, v[118:121] offset:27648
	v_mfma_f32_32x32x16_bf16 v[18:33], v[142:145], v[146:149], v[18:33]
	ds_write_b128 v223, v[122:125] offset:18432
	ds_write_b128 v223, v[126:129] offset:27648
	v_mfma_f32_32x32x16_bf16 v[2:17], v[150:153], v[146:149], v[2:17]
	global_load_dwordx4 v[114:117], v210, s[0:1] offset:1408
	global_load_dwordx4 v[118:121], v210, s[2:3] offset:1408
	global_load_dwordx4 v[122:125], v214, s[4:5] offset:1408
	global_load_dwordx4 v[126:129], v214, s[6:7] offset:1408
	global_load_dwordx4 v[178:181], v221, s[8:9]
	global_load_dwordx4 v[182:185], v221, s[8:9] offset:16
	global_load_dwordx4 v[186:189], v221, s[8:9] offset:64
	global_load_dwordx4 v[190:193], v221, s[8:9] offset:80
	ds_read_b128 v[130:133], v219
	ds_read_b128 v[134:137], v220
	ds_read_b128 v[138:141], v219 offset:4608
	s_waitcnt lgkmcnt(11)
	v_mfma_f32_32x32x16_bf16 v[18:33], v[154:157], v[158:161], v[18:33]
	ds_read_b128 v[142:145], v219 offset:32
	ds_read_b128 v[146:149], v220 offset:32
	ds_read_b128 v[150:153], v219 offset:4640
	s_waitcnt lgkmcnt(13)
	v_mfma_f32_32x32x16_bf16 v[2:17], v[162:165], v[158:161], v[2:17]
	s_waitcnt lgkmcnt(11)
	v_mfma_f32_32x32x16_bf16 v[18:33], v[166:169], v[170:173], v[18:33]
	s_waitcnt lgkmcnt(10)
	v_mfma_f32_32x32x16_bf16 v[2:17], v[174:177], v[170:173], v[2:17]
	s_waitcnt lgkmcnt(0)
	s_barrier
	ds_read_b128 v[154:157], v219 offset:64
	ds_read_b128 v[158:161], v220 offset:64
	ds_read_b128 v[162:165], v219 offset:4672
	v_mfma_f32_32x32x16_bf16 v[18:33], v[130:133], v[134:137], v[18:33]
	ds_read_b128 v[166:169], v219 offset:96
	ds_read_b128 v[170:173], v220 offset:96
	ds_read_b128 v[174:177], v219 offset:4704
	v_mfma_f32_32x32x16_bf16 v[2:17], v[138:141], v[134:137], v[2:17]
	s_waitcnt vmcnt(16)
	ds_write_b128 v218, v[66:69] offset:36864
	ds_write_b128 v218, v[70:73] offset:46080
	v_mfma_f32_32x32x16_bf16 v[18:33], v[142:145], v[146:149], v[18:33]
	ds_write_b128 v223, v[74:77] offset:36864
	ds_write_b128 v223, v[78:81] offset:46080
	v_mfma_f32_32x32x16_bf16 v[2:17], v[150:153], v[146:149], v[2:17]
	s_mul_i32 s52, s58, 0x100
	s_add_u32 s0, s20, s52
	s_addc_u32 s1, s21, 0
	s_add_u32 s2, s0, 0x4000
	s_addc_u32 s3, s1, 0
	s_mul_i32 s52, s59, 0x100
	s_add_u32 s4, s36, s52
	s_addc_u32 s5, s37, 0
	s_add_u32 s6, s4, 0x4000
	s_addc_u32 s7, s5, 0
	global_load_dwordx4 v[66:69], v211, s[0:1]
	global_load_dwordx4 v[70:73], v211, s[2:3]
	global_load_dwordx4 v[74:77], v215, s[4:5]
	global_load_dwordx4 v[78:81], v215, s[6:7]
	ds_read_b128 v[130:133], v219 offset:18432
	ds_read_b128 v[134:137], v220 offset:18432
	ds_read_b128 v[138:141], v219 offset:23040
	s_waitcnt lgkmcnt(11)
	v_mfma_f32_32x32x16_bf16 v[18:33], v[154:157], v[158:161], v[18:33]
	ds_read_b128 v[142:145], v219 offset:18464
	ds_read_b128 v[146:149], v220 offset:18464
	ds_read_b128 v[150:153], v219 offset:23072
	s_waitcnt lgkmcnt(13)
	v_mfma_f32_32x32x16_bf16 v[2:17], v[162:165], v[158:161], v[2:17]
	s_waitcnt lgkmcnt(11)
	v_mfma_f32_32x32x16_bf16 v[18:33], v[166:169], v[170:173], v[18:33]
	s_waitcnt lgkmcnt(10)
	v_mfma_f32_32x32x16_bf16 v[2:17], v[174:177], v[170:173], v[2:17]
	s_waitcnt lgkmcnt(0)
	s_barrier
	ds_read_b128 v[154:157], v219 offset:18496
	ds_read_b128 v[158:161], v220 offset:18496
	ds_read_b128 v[162:165], v219 offset:23104
	v_mfma_f32_32x32x16_bf16 v[18:33], v[130:133], v[134:137], v[18:33]
	ds_read_b128 v[166:169], v219 offset:18528
	ds_read_b128 v[170:173], v220 offset:18528
	ds_read_b128 v[174:177], v219 offset:23136
	v_mfma_f32_32x32x16_bf16 v[2:17], v[138:141], v[134:137], v[2:17]
	s_waitcnt vmcnt(16)
	ds_write_b128 v218, v[82:85]
	ds_write_b128 v218, v[86:89] offset:9216
	v_mfma_f32_32x32x16_bf16 v[18:33], v[142:145], v[146:149], v[18:33]
	ds_write_b128 v223, v[90:93]
	ds_write_b128 v223, v[94:97] offset:9216
	v_mfma_f32_32x32x16_bf16 v[2:17], v[150:153], v[146:149], v[2:17]
	global_load_dwordx4 v[82:85], v211, s[0:1] offset:128
	global_load_dwordx4 v[86:89], v211, s[2:3] offset:128
	global_load_dwordx4 v[90:93], v215, s[4:5] offset:128
	global_load_dwordx4 v[94:97], v215, s[6:7] offset:128
	global_load_dwordx4 v[194:197], v221, s[8:9] offset:2048
	global_load_dwordx4 v[198:201], v221, s[8:9] offset:2064
	global_load_dwordx4 v[202:205], v221, s[8:9] offset:2112
	global_load_dwordx4 v[206:209], v221, s[8:9] offset:2128
	ds_read_b128 v[130:133], v219 offset:36864
	ds_read_b128 v[134:137], v220 offset:36864
	ds_read_b128 v[138:141], v219 offset:41472
	s_waitcnt lgkmcnt(11)
	v_mfma_f32_32x32x16_bf16 v[18:33], v[154:157], v[158:161], v[18:33]
	ds_read_b128 v[142:145], v219 offset:36896
	ds_read_b128 v[146:149], v220 offset:36896
	ds_read_b128 v[150:153], v219 offset:41504
	s_waitcnt lgkmcnt(13)
	v_mfma_f32_32x32x16_bf16 v[2:17], v[162:165], v[158:161], v[2:17]
	s_waitcnt lgkmcnt(11)
	v_mfma_f32_32x32x16_bf16 v[18:33], v[166:169], v[170:173], v[18:33]
	s_waitcnt lgkmcnt(10)
	v_mfma_f32_32x32x16_bf16 v[2:17], v[174:177], v[170:173], v[2:17]
	s_waitcnt lgkmcnt(0)
	s_barrier
; DI f32x16 mfma(bf16x8 a, bf16x8 b, f32x16 c) { return __builtin_amdgcn_mfma_f32_32x32x16_bf16(a, b, c, 0, 0, 0); }
; template <bool RFA, bool RFB, class LA, class LB, class EPI>
; DI void gemm_tile2s(u16* smem, int nk, LA la, LB lb, EPI epi) {
;     ...
;   auto ld = [&](u32x4 (&ra)[2], u32x4 (&rb)[2], int kt) __attribute__((always_inline)) {
;     const int k0 = kt * 64;
; #pragma unroll
;     for (int i = 0; i < 2; ++i) { const int c = tid + NTH * i; ra[i] = la(A_ROW(c), k0 + A_KC(c) * 8); rb[i] = lb(B_ROW(c), k0 + B_KC(c) * 8); }
;   };
;   auto stl = [&](u32x4 (&ra)[2], u32x4 (&rb)[2], int buf) __attribute__((always_inline)) {
; #pragma unroll
;     for (int i = 0; i < 2; ++i) {
;       const int c = tid + NTH * i;
;       *(u32x4*)(As + buf * TILE_ELEMS + A_ROW(c) * LDT + A_KC(c) * 8) = ra[i];
;       *(u32x4*)(Bs + buf * TILE_ELEMS + B_ROW(c) * LDT + B_KC(c) * 8) = rb[i];
;     }
;   };
;   auto compute = [&](int buf) __attribute__((always_inline)) {
;     const u16* Ab = As + buf * TILE_ELEMS + (wm * 64 + lr) * LDT + lh * 8;
;     const u16* Bb = Bs + buf * TILE_ELEMS + (wn * 32 + lr) * LDT + lh * 8;
; #pragma unroll
;     for (int ks = 0; ks < 4; ++ks) {
;       const bf16x8 a0 = *(const bf16x8*)(Ab + ks * 16);
;       const bf16x8 a1 = *(const bf16x8*)(Ab + 32 * LDT + ks * 16);
;       const bf16x8 b = *(const bf16x8*)(Bb + ks * 16);
;       acc[0] = mfma(a0, b, acc[0]);
;       acc[1] = mfma(a1, b, acc[1]);
;     }
;   };
;   ld(ra0, rb0, 0);
;   if (nk > 1) ld(ra1, rb1, 1);
;   stl(ra0, rb0, 0);
;   if (nk > 2) ld(ra0, rb0, 2);
;   __syncthreads();
; #pragma unroll 1
;   for (int kt = 0; kt < nk; kt += 2) {
;     compute(0);
;     if (kt + 1 < nk) { stl(ra1, rb1, 1); if (kt + 3 < nk) ld(ra1, rb1, kt + 3); }
;     __syncthreads();
;     if (kt + 1 < nk) {
;       compute(1);
;       if (kt + 2 < nk) { stl(ra0, rb0, 0); if (kt + 4 < nk) ld(ra0, rb0, kt + 4); }
;       __syncthreads();
	ds_read_b128 v[154:157], v219 offset:36928
	ds_read_b128 v[158:161], v220 offset:36928
	ds_read_b128 v[162:165], v219 offset:41536
	v_mfma_f32_32x32x16_bf16 v[18:33], v[130:133], v[134:137], v[18:33]
	ds_read_b128 v[166:169], v219 offset:36960
	ds_read_b128 v[170:173], v220 offset:36960
	ds_read_b128 v[174:177], v219 offset:41568
	v_mfma_f32_32x32x16_bf16 v[2:17], v[138:141], v[134:137], v[2:17]
	s_waitcnt vmcnt(20)
	ds_write_b128 v218, v[98:101] offset:18432
	ds_write_b128 v218, v[102:105] offset:27648
	v_mfma_f32_32x32x16_bf16 v[18:33], v[142:145], v[146:149], v[18:33]
	ds_write_b128 v223, v[106:109] offset:18432
	ds_write_b128 v223, v[110:113] offset:27648
	v_mfma_f32_32x32x16_bf16 v[2:17], v[150:153], v[146:149], v[2:17]
	s_mul_i32 s52, s58, 0x300
	s_add_u32 s0, s22, s52
	s_addc_u32 s1, s23, 0
	s_add_u32 s2, s0, 0xc000
	s_addc_u32 s3, s1, 0
	s_mul_i32 s52, s59, 0x300
	s_add_u32 s4, s38, s52
	s_addc_u32 s5, s39, 0
	s_add_u32 s6, s4, 0xc000
	s_addc_u32 s7, s5, 0
	global_load_dwordx4 v[98:101], v212, s[0:1]
	global_load_dwordx4 v[102:105], v212, s[2:3]
	global_load_dwordx4 v[106:109], v216, s[4:5]
	global_load_dwordx4 v[110:113], v216, s[6:7]
	ds_read_b128 v[130:133], v219
	ds_read_b128 v[134:137], v220
	ds_read_b128 v[138:141], v219 offset:4608
	s_waitcnt lgkmcnt(11)
	v_mfma_f32_32x32x16_bf16 v[18:33], v[154:157], v[158:161], v[18:33]
	ds_read_b128 v[142:145], v219 offset:32
	ds_read_b128 v[146:149], v220 offset:32
	ds_read_b128 v[150:153], v219 offset:4640
	s_waitcnt lgkmcnt(13)
	v_mfma_f32_32x32x16_bf16 v[2:17], v[162:165], v[158:161], v[2:17]
	s_waitcnt lgkmcnt(11)
	v_mfma_f32_32x32x16_bf16 v[18:33], v[166:169], v[170:173], v[18:33]
	s_waitcnt lgkmcnt(10)
	v_mfma_f32_32x32x16_bf16 v[2:17], v[174:177], v[170:173], v[2:17]
	s_waitcnt lgkmcnt(0)
	s_barrier
	ds_read_b128 v[154:157], v219 offset:64
	ds_read_b128 v[158:161], v220 offset:64
	ds_read_b128 v[162:165], v219 offset:4672
	v_mfma_f32_32x32x16_bf16 v[18:33], v[130:133], v[134:137], v[18:33]
	ds_read_b128 v[166:169], v219 offset:96
	ds_read_b128 v[170:173], v220 offset:96
	ds_read_b128 v[174:177], v219 offset:4704
	v_mfma_f32_32x32x16_bf16 v[2:17], v[138:141], v[134:137], v[2:17]
	s_waitcnt vmcnt(20)
	ds_write_b128 v218, v[114:117] offset:36864
	ds_write_b128 v218, v[118:121] offset:46080
	v_mfma_f32_32x32x16_bf16 v[18:33], v[142:145], v[146:149], v[18:33]
	ds_write_b128 v223, v[122:125] offset:36864
	ds_write_b128 v223, v[126:129] offset:46080
	v_mfma_f32_32x32x16_bf16 v[2:17], v[150:153], v[146:149], v[2:17]
	global_load_dwordx4 v[114:117], v212, s[0:1] offset:128
	global_load_dwordx4 v[118:121], v212, s[2:3] offset:128
	global_load_dwordx4 v[122:125], v216, s[4:5] offset:128
	global_load_dwordx4 v[126:129], v216, s[6:7] offset:128
	ds_read_b128 v[130:133], v219 offset:18432
	ds_read_b128 v[134:137], v220 offset:18432
	ds_read_b128 v[138:141], v219 offset:23040
	s_waitcnt lgkmcnt(11)
	v_mfma_f32_32x32x16_bf16 v[18:33], v[154:157], v[158:161], v[18:33]
	ds_read_b128 v[142:145], v219 offset:18464
	ds_read_b128 v[146:149], v220 offset:18464
	ds_read_b128 v[150:153], v219 offset:23072
	s_waitcnt lgkmcnt(13)
	v_mfma_f32_32x32x16_bf16 v[2:17], v[162:165], v[158:161], v[2:17]
	s_waitcnt lgkmcnt(11)
	v_mfma_f32_32x32x16_bf16 v[18:33], v[166:169], v[170:173], v[18:33]
	s_waitcnt lgkmcnt(10)
	v_mfma_f32_32x32x16_bf16 v[2:17], v[174:177], v[170:173], v[2:17]
	s_waitcnt lgkmcnt(0)
	s_barrier
	ds_read_b128 v[154:157], v219 offset:18496
	ds_read_b128 v[158:161], v220 offset:18496
	ds_read_b128 v[162:165], v219 offset:23104
	v_mfma_f32_32x32x16_bf16 v[18:33], v[130:133], v[134:137], v[18:33]
	ds_read_b128 v[166:169], v219 offset:18528
	ds_read_b128 v[170:173], v220 offset:18528
	ds_read_b128 v[174:177], v219 offset:23136
	v_mfma_f32_32x32x16_bf16 v[2:17], v[138:141], v[134:137], v[2:17]
	s_waitcnt vmcnt(16)
	ds_write_b128 v218, v[66:69]
	ds_write_b128 v218, v[70:73] offset:9216
	v_mfma_f32_32x32x16_bf16 v[18:33], v[142:145], v[146:149], v[18:33]
	ds_write_b128 v223, v[74:77]
	ds_write_b128 v223, v[78:81] offset:9216
	v_mfma_f32_32x32x16_bf16 v[2:17], v[150:153], v[146:149], v[2:17]
	global_load_dwordx4 v[66:69], v212, s[0:1] offset:256
	global_load_dwordx4 v[70:73], v212, s[2:3] offset:256
	global_load_dwordx4 v[74:77], v216, s[4:5] offset:256
	global_load_dwordx4 v[78:81], v216, s[6:7] offset:256
	ds_read_b128 v[130:133], v219 offset:36864
	ds_read_b128 v[134:137], v220 offset:36864
	ds_read_b128 v[138:141], v219 offset:41472
	s_waitcnt lgkmcnt(11)
	v_mfma_f32_32x32x16_bf16 v[18:33], v[154:157], v[158:161], v[18:33]
	ds_read_b128 v[142:145], v219 offset:36896
	ds_read_b128 v[146:149], v220 offset:36896
	ds_read_b128 v[150:153], v219 offset:41504
	s_waitcnt lgkmcnt(13)
	v_mfma_f32_32x32x16_bf16 v[2:17], v[162:165], v[158:161], v[2:17]
	s_waitcnt lgkmcnt(11)
	v_mfma_f32_32x32x16_bf16 v[18:33], v[166:169], v[170:173], v[18:33]
	s_waitcnt lgkmcnt(10)
	v_mfma_f32_32x32x16_bf16 v[2:17], v[174:177], v[170:173], v[2:17]
	s_waitcnt lgkmcnt(0)
	s_barrier
; template <bool RFA, bool RFB, class LA, class LB, class EPI>
; DI void gemm_tile2s(u16* smem, int nk, LA la, LB lb, EPI epi) {
;     ...
;   auto ld = [&](u32x4 (&ra)[2], u32x4 (&rb)[2], int kt) __attribute__((always_inline)) {
;     const int k0 = kt * 64;
; #pragma unroll
;     for (int i = 0; i < 2; ++i) { const int c = tid + NTH * i; ra[i] = la(A_ROW(c), k0 + A_KC(c) * 8); rb[i] = lb(B_ROW(c), k0 + B_KC(c) * 8); }
;   };
;   auto stl = [&](u32x4 (&ra)[2], u32x4 (&rb)[2], int buf) __attribute__((always_inline)) {
; #pragma unroll
;     for (int i = 0; i < 2; ++i) {
;       const int c = tid + NTH * i;
;       *(u32x4*)(As + buf * TILE_ELEMS + A_ROW(c) * LDT + A_KC(c) * 8) = ra[i];
;       *(u32x4*)(Bs + buf * TILE_ELEMS + B_ROW(c) * LDT + B_KC(c) * 8) = rb[i];
;     }
;   };
;   auto compute = [&](int buf) __attribute__((always_inline)) {
;     const u16* Ab = As + buf * TILE_ELEMS + (wm * 64 + lr) * LDT + lh * 8;
;     const u16* Bb = Bs + buf * TILE_ELEMS + (wn * 32 + lr) * LDT + lh * 8;
; #pragma unroll
;     for (int ks = 0; ks < 4; ++ks) {
;       const bf16x8 a0 = *(const bf16x8*)(Ab + ks * 16);
;       const bf16x8 a1 = *(const bf16x8*)(Ab + 32 * LDT + ks * 16);
;       const bf16x8 b = *(const bf16x8*)(Bb + ks * 16);
;       acc[0] = mfma(a0, b, acc[0]);
;       acc[1] = mfma(a1, b, acc[1]);
;     }
;   };
;   ld(ra0, rb0, 0);
;   if (nk > 1) ld(ra1, rb1, 1);
;   stl(ra0, rb0, 0);
;   if (nk > 2) ld(ra0, rb0, 2);
;   __syncthreads();
; #pragma unroll 1
;   for (int kt = 0; kt < nk; kt += 2) {
;     compute(0);
;     if (kt + 1 < nk) { stl(ra1, rb1, 1); if (kt + 3 < nk) ld(ra1, rb1, kt + 3); }
;     __syncthreads();
;     if (kt + 1 < nk) {
;       compute(1);
;       if (kt + 2 < nk) { stl(ra0, rb0, 0); if (kt + 4 < nk) ld(ra0, rb0, kt + 4); }
;       __syncthreads();
; template <class ACC>
; DI void merge_branch(const Prm& p, u16* smem, const u16* W, const u16* X, int ld, int bi, int n0, int m0, ACC& macc) {
;     ...
;   auto epi = [&](f32x16 (&acc)[2], int wm, int wn, int lane) __attribute__((always_inline)) {
;     const int lr = lane & 31, lh = lane >> 5;
;     const int tok = m0 + wn * 32 + lr;
; #pragma unroll
;     for (int i = 0; i < 2; ++i)
; #pragma unroll
;       for (int h2 = 0; h2 < 2; ++h2) {
;         const int n = n0 + wm * 64 + i * 32 + 16 * lh + 8 * h2;
;         const u32x4 gz = *(const u32x4*)(p.zg + (size_t)tok * 4096 + bi * 1024 + n);
	ds_read_b128 v[154:157], v219 offset:36928
	ds_read_b128 v[158:161], v220 offset:36928
	ds_read_b128 v[162:165], v219 offset:41536
	v_mfma_f32_32x32x16_bf16 v[18:33], v[130:133], v[134:137], v[18:33]
	ds_read_b128 v[166:169], v219 offset:36960
	ds_read_b128 v[170:173], v220 offset:36960
	ds_read_b128 v[174:177], v219 offset:41568
	v_mfma_f32_32x32x16_bf16 v[2:17], v[138:141], v[134:137], v[2:17]
	s_waitcnt vmcnt(16)
	ds_write_b128 v218, v[82:85] offset:18432
	ds_write_b128 v218, v[86:89] offset:27648
	v_mfma_f32_32x32x16_bf16 v[18:33], v[142:145], v[146:149], v[18:33]
	ds_write_b128 v223, v[90:93] offset:18432
	ds_write_b128 v223, v[94:97] offset:27648
	v_mfma_f32_32x32x16_bf16 v[2:17], v[150:153], v[146:149], v[2:17]
	global_load_dwordx4 v[82:85], v212, s[0:1] offset:384
	global_load_dwordx4 v[86:89], v212, s[2:3] offset:384
	global_load_dwordx4 v[90:93], v216, s[4:5] offset:384
	global_load_dwordx4 v[94:97], v216, s[6:7] offset:384
	ds_read_b128 v[130:133], v219
	ds_read_b128 v[134:137], v220
	ds_read_b128 v[138:141], v219 offset:4608
	s_waitcnt lgkmcnt(11)
	v_mfma_f32_32x32x16_bf16 v[18:33], v[154:157], v[158:161], v[18:33]
	ds_read_b128 v[142:145], v219 offset:32
	ds_read_b128 v[146:149], v220 offset:32
	ds_read_b128 v[150:153], v219 offset:4640
	s_waitcnt lgkmcnt(13)
	v_mfma_f32_32x32x16_bf16 v[2:17], v[162:165], v[158:161], v[2:17]
	s_waitcnt lgkmcnt(11)
	v_mfma_f32_32x32x16_bf16 v[18:33], v[166:169], v[170:173], v[18:33]
	s_waitcnt lgkmcnt(10)
	v_mfma_f32_32x32x16_bf16 v[2:17], v[174:177], v[170:173], v[2:17]
	s_waitcnt vmcnt(28)
	s_nop 15
	v_lshlrev_b32_e32 v226, 16, v178
	v_and_b32_e32 v227, 0xffff0000, v178
	v_pk_mul_f32 v[34:35], v[226:227], v[18:19]
	v_lshlrev_b32_e32 v228, 16, v179
	v_and_b32_e32 v229, 0xffff0000, v179
	v_pk_mul_f32 v[36:37], v[228:229], v[20:21]
	v_lshlrev_b32_e32 v234, 16, v180
	v_and_b32_e32 v235, 0xffff0000, v180
	v_pk_mul_f32 v[38:39], v[234:235], v[22:23]
	v_lshlrev_b32_e32 v236, 16, v181
	v_and_b32_e32 v237, 0xffff0000, v181
	v_pk_mul_f32 v[40:41], v[236:237], v[24:25]
	v_lshlrev_b32_e32 v226, 16, v182
	v_and_b32_e32 v227, 0xffff0000, v182
	v_pk_mul_f32 v[42:43], v[226:227], v[26:27]
	v_lshlrev_b32_e32 v228, 16, v183
	v_and_b32_e32 v229, 0xffff0000, v183
	v_pk_mul_f32 v[44:45], v[228:229], v[28:29]
	v_lshlrev_b32_e32 v234, 16, v184
	v_and_b32_e32 v235, 0xffff0000, v184
	v_pk_mul_f32 v[46:47], v[234:235], v[30:31]
	v_lshlrev_b32_e32 v236, 16, v185
	v_and_b32_e32 v237, 0xffff0000, v185
	v_pk_mul_f32 v[48:49], v[236:237], v[32:33]
	v_lshlrev_b32_e32 v226, 16, v186
	v_and_b32_e32 v227, 0xffff0000, v186
	v_pk_mul_f32 v[50:51], v[226:227], v[2:3]
	v_lshlrev_b32_e32 v228, 16, v187
	v_and_b32_e32 v229, 0xffff0000, v187
	v_pk_mul_f32 v[52:53], v[228:229], v[4:5]
	v_lshlrev_b32_e32 v234, 16, v188
	v_and_b32_e32 v235, 0xffff0000, v188
	v_pk_mul_f32 v[54:55], v[234:235], v[6:7]
	v_lshlrev_b32_e32 v236, 16, v189
	v_and_b32_e32 v237, 0xffff0000, v189
	v_pk_mul_f32 v[56:57], v[236:237], v[8:9]
	v_lshlrev_b32_e32 v226, 16, v190
	v_and_b32_e32 v227, 0xffff0000, v190
	v_pk_mul_f32 v[58:59], v[226:227], v[10:11]
	v_lshlrev_b32_e32 v228, 16, v191
	v_and_b32_e32 v229, 0xffff0000, v191
	v_pk_mul_f32 v[60:61], v[228:229], v[12:13]
	v_lshlrev_b32_e32 v234, 16, v192
	v_and_b32_e32 v235, 0xffff0000, v192
	v_pk_mul_f32 v[62:63], v[234:235], v[14:15]
	v_lshlrev_b32_e32 v236, 16, v193
	v_and_b32_e32 v237, 0xffff0000, v193
	v_pk_mul_f32 v[64:65], v[236:237], v[16:17]
	s_waitcnt lgkmcnt(0)
	s_barrier
	ds_read_b128 v[154:157], v219 offset:64
	ds_read_b128 v[158:161], v220 offset:64
	ds_read_b128 v[162:165], v219 offset:4672
	v_mfma_f32_32x32x16_bf16 v[18:33], v[130:133], v[134:137], 0
	ds_read_b128 v[166:169], v219 offset:96
	ds_read_b128 v[170:173], v220 offset:96
	ds_read_b128 v[174:177], v219 offset:4704
	v_mfma_f32_32x32x16_bf16 v[2:17], v[138:141], v[134:137], 0
	s_waitcnt vmcnt(12)
	ds_write_b128 v218, v[98:101] offset:36864
	ds_write_b128 v218, v[102:105] offset:46080
	v_mfma_f32_32x32x16_bf16 v[18:33], v[142:145], v[146:149], v[18:33]
	ds_write_b128 v223, v[106:109] offset:36864
	ds_write_b128 v223, v[110:113] offset:46080
	v_mfma_f32_32x32x16_bf16 v[2:17], v[150:153], v[146:149], v[2:17]
	global_load_dwordx4 v[98:101], v212, s[0:1] offset:512
	global_load_dwordx4 v[102:105], v212, s[2:3] offset:512
	global_load_dwordx4 v[106:109], v216, s[4:5] offset:512
	global_load_dwordx4 v[110:113], v216, s[6:7] offset:512
	global_load_dwordx4 v[178:181], v221, s[10:11]
	global_load_dwordx4 v[182:185], v221, s[10:11] offset:16
	global_load_dwordx4 v[186:189], v221, s[10:11] offset:64
	global_load_dwordx4 v[190:193], v221, s[10:11] offset:80
	ds_read_b128 v[130:133], v219 offset:18432
	ds_read_b128 v[134:137], v220 offset:18432
	ds_read_b128 v[138:141], v219 offset:23040
	s_waitcnt lgkmcnt(11)
	v_mfma_f32_32x32x16_bf16 v[18:33], v[154:157], v[158:161], v[18:33]
	ds_read_b128 v[142:145], v219 offset:18464
	ds_read_b128 v[146:149], v220 offset:18464
	ds_read_b128 v[150:153], v219 offset:23072
	s_waitcnt lgkmcnt(13)
	v_mfma_f32_32x32x16_bf16 v[2:17], v[162:165], v[158:161], v[2:17]
	s_waitcnt lgkmcnt(11)
	v_mfma_f32_32x32x16_bf16 v[18:33], v[166:169], v[170:173], v[18:33]
	s_waitcnt lgkmcnt(10)
	v_mfma_f32_32x32x16_bf16 v[2:17], v[174:177], v[170:173], v[2:17]
	s_waitcnt lgkmcnt(0)
	s_barrier
; template <bool RFA, bool RFB, class LA, class LB, class EPI>
; DI void gemm_tile2s(u16* smem, int nk, LA la, LB lb, EPI epi) {
;     ...
;   auto ld = [&](u32x4 (&ra)[2], u32x4 (&rb)[2], int kt) __attribute__((always_inline)) {
;     const int k0 = kt * 64;
; #pragma unroll
;     for (int i = 0; i < 2; ++i) { const int c = tid + NTH * i; ra[i] = la(A_ROW(c), k0 + A_KC(c) * 8); rb[i] = lb(B_ROW(c), k0 + B_KC(c) * 8); }
;   };
;   auto stl = [&](u32x4 (&ra)[2], u32x4 (&rb)[2], int buf) __attribute__((always_inline)) {
; #pragma unroll
;     for (int i = 0; i < 2; ++i) {
;       const int c = tid + NTH * i;
;       *(u32x4*)(As + buf * TILE_ELEMS + A_ROW(c) * LDT + A_KC(c) * 8) = ra[i];
;       *(u32x4*)(Bs + buf * TILE_ELEMS + B_ROW(c) * LDT + B_KC(c) * 8) = rb[i];
;     }
;   };
;   auto compute = [&](int buf) __attribute__((always_inline)) {
;     const u16* Ab = As + buf * TILE_ELEMS + (wm * 64 + lr) * LDT + lh * 8;
;     const u16* Bb = Bs + buf * TILE_ELEMS + (wn * 32 + lr) * LDT + lh * 8;
; #pragma unroll
;     for (int ks = 0; ks < 4; ++ks) {
;       const bf16x8 a0 = *(const bf16x8*)(Ab + ks * 16);
;       const bf16x8 a1 = *(const bf16x8*)(Ab + 32 * LDT + ks * 16);
;       const bf16x8 b = *(const bf16x8*)(Bb + ks * 16);
;       acc[0] = mfma(a0, b, acc[0]);
;       acc[1] = mfma(a1, b, acc[1]);
;     }
;   };
;   ld(ra0, rb0, 0);
;   if (nk > 1) ld(ra1, rb1, 1);
;   stl(ra0, rb0, 0);
;   if (nk > 2) ld(ra0, rb0, 2);
;   __syncthreads();
; #pragma unroll 1
;   for (int kt = 0; kt < nk; kt += 2) {
;     compute(0);
;     if (kt + 1 < nk) { stl(ra1, rb1, 1); if (kt + 3 < nk) ld(ra1, rb1, kt + 3); }
;     __syncthreads();
;     if (kt + 1 < nk) {
;       compute(1);
;       if (kt + 2 < nk) { stl(ra0, rb0, 0); if (kt + 4 < nk) ld(ra0, rb0, kt + 4); }
;       __syncthreads();
; template <class ACC>
; DI void merge_branch(const Prm& p, u16* smem, const u16* W, const u16* X, int ld, int bi, int n0, int m0, ACC& macc) {
;     ...
;   auto epi = [&](f32x16 (&acc)[2], int wm, int wn, int lane) __attribute__((always_inline)) {
;     const int lr = lane & 31, lh = lane >> 5;
;     const int tok = m0 + wn * 32 + lr;
; #pragma unroll
;     for (int i = 0; i < 2; ++i)
; #pragma unroll
;       for (int h2 = 0; h2 < 2; ++h2) {
;         const int n = n0 + wm * 64 + i * 32 + 16 * lh + 8 * h2;
;         const u32x4 gz = *(const u32x4*)(p.zg + (size_t)tok * 4096 + bi * 1024 + n);
	ds_read_b128 v[154:157], v219 offset:18496
	ds_read_b128 v[158:161], v220 offset:18496
	ds_read_b128 v[162:165], v219 offset:23104
	v_mfma_f32_32x32x16_bf16 v[18:33], v[130:133], v[134:137], v[18:33]
	ds_read_b128 v[166:169], v219 offset:18528
	ds_read_b128 v[170:173], v220 offset:18528
	ds_read_b128 v[174:177], v219 offset:23136
	v_mfma_f32_32x32x16_bf16 v[2:17], v[138:141], v[134:137], v[2:17]
	s_waitcnt vmcnt(16)
	ds_write_b128 v218, v[114:117]
	ds_write_b128 v218, v[118:121] offset:9216
	v_mfma_f32_32x32x16_bf16 v[18:33], v[142:145], v[146:149], v[18:33]
	ds_write_b128 v223, v[122:125]
	ds_write_b128 v223, v[126:129] offset:9216
	v_mfma_f32_32x32x16_bf16 v[2:17], v[150:153], v[146:149], v[2:17]
	global_load_dwordx4 v[114:117], v212, s[0:1] offset:640
	global_load_dwordx4 v[118:121], v212, s[2:3] offset:640
	global_load_dwordx4 v[122:125], v216, s[4:5] offset:640
	global_load_dwordx4 v[126:129], v216, s[6:7] offset:640
	ds_read_b128 v[130:133], v219 offset:36864
	ds_read_b128 v[134:137], v220 offset:36864
	ds_read_b128 v[138:141], v219 offset:41472
	s_waitcnt lgkmcnt(11)
	v_mfma_f32_32x32x16_bf16 v[18:33], v[154:157], v[158:161], v[18:33]
	ds_read_b128 v[142:145], v219 offset:36896
	ds_read_b128 v[146:149], v220 offset:36896
	ds_read_b128 v[150:153], v219 offset:41504
	s_waitcnt lgkmcnt(13)
	v_mfma_f32_32x32x16_bf16 v[2:17], v[162:165], v[158:161], v[2:17]
	s_waitcnt lgkmcnt(11)
	v_mfma_f32_32x32x16_bf16 v[18:33], v[166:169], v[170:173], v[18:33]
	s_waitcnt lgkmcnt(10)
	v_mfma_f32_32x32x16_bf16 v[2:17], v[174:177], v[170:173], v[2:17]
	s_waitcnt vmcnt(28)
	s_nop 15
	v_lshlrev_b32_e32 v226, 16, v194
	v_and_b32_e32 v227, 0xffff0000, v194
	v_pk_fma_f32 v[34:35], v[226:227], v[18:19], v[34:35]
	v_lshlrev_b32_e32 v228, 16, v195
	v_and_b32_e32 v229, 0xffff0000, v195
	v_pk_fma_f32 v[36:37], v[228:229], v[20:21], v[36:37]
	v_lshlrev_b32_e32 v234, 16, v196
	v_and_b32_e32 v235, 0xffff0000, v196
	v_pk_fma_f32 v[38:39], v[234:235], v[22:23], v[38:39]
	v_lshlrev_b32_e32 v236, 16, v197
	v_and_b32_e32 v237, 0xffff0000, v197
	v_pk_fma_f32 v[40:41], v[236:237], v[24:25], v[40:41]
	v_lshlrev_b32_e32 v226, 16, v198
	v_and_b32_e32 v227, 0xffff0000, v198
	v_pk_fma_f32 v[42:43], v[226:227], v[26:27], v[42:43]
	v_lshlrev_b32_e32 v228, 16, v199
	v_and_b32_e32 v229, 0xffff0000, v199
	v_pk_fma_f32 v[44:45], v[228:229], v[28:29], v[44:45]
	v_lshlrev_b32_e32 v234, 16, v200
	v_and_b32_e32 v235, 0xffff0000, v200
	v_pk_fma_f32 v[46:47], v[234:235], v[30:31], v[46:47]
	v_lshlrev_b32_e32 v236, 16, v201
	v_and_b32_e32 v237, 0xffff0000, v201
	v_pk_fma_f32 v[48:49], v[236:237], v[32:33], v[48:49]
	v_lshlrev_b32_e32 v226, 16, v202
	v_and_b32_e32 v227, 0xffff0000, v202
	v_pk_fma_f32 v[50:51], v[226:227], v[2:3], v[50:51]
	v_lshlrev_b32_e32 v228, 16, v203
	v_and_b32_e32 v229, 0xffff0000, v203
	v_pk_fma_f32 v[52:53], v[228:229], v[4:5], v[52:53]
	v_lshlrev_b32_e32 v234, 16, v204
	v_and_b32_e32 v235, 0xffff0000, v204
	v_pk_fma_f32 v[54:55], v[234:235], v[6:7], v[54:55]
	v_lshlrev_b32_e32 v236, 16, v205
	v_and_b32_e32 v237, 0xffff0000, v205
	v_pk_fma_f32 v[56:57], v[236:237], v[8:9], v[56:57]
	v_lshlrev_b32_e32 v226, 16, v206
	v_and_b32_e32 v227, 0xffff0000, v206
	v_pk_fma_f32 v[58:59], v[226:227], v[10:11], v[58:59]
	v_lshlrev_b32_e32 v228, 16, v207
	v_and_b32_e32 v229, 0xffff0000, v207
	v_pk_fma_f32 v[60:61], v[228:229], v[12:13], v[60:61]
	v_lshlrev_b32_e32 v234, 16, v208
	v_and_b32_e32 v235, 0xffff0000, v208
	v_pk_fma_f32 v[62:63], v[234:235], v[14:15], v[62:63]
	v_lshlrev_b32_e32 v236, 16, v209
	v_and_b32_e32 v237, 0xffff0000, v209
	v_pk_fma_f32 v[64:65], v[236:237], v[16:17], v[64:65]
	s_waitcnt lgkmcnt(0)
	s_barrier
	ds_read_b128 v[154:157], v219 offset:36928
	ds_read_b128 v[158:161], v220 offset:36928
	ds_read_b128 v[162:165], v219 offset:41536
	v_mfma_f32_32x32x16_bf16 v[18:33], v[130:133], v[134:137], 0
	ds_read_b128 v[166:169], v219 offset:36960
	ds_read_b128 v[170:173], v220 offset:36960
	ds_read_b128 v[174:177], v219 offset:41568
	v_mfma_f32_32x32x16_bf16 v[2:17], v[138:141], v[134:137], 0
	s_waitcnt vmcnt(16)
	ds_write_b128 v218, v[66:69] offset:18432
	ds_write_b128 v218, v[70:73] offset:27648
	v_mfma_f32_32x32x16_bf16 v[18:33], v[142:145], v[146:149], v[18:33]
	ds_write_b128 v223, v[74:77] offset:18432
	ds_write_b128 v223, v[78:81] offset:27648
	v_mfma_f32_32x32x16_bf16 v[2:17], v[150:153], v[146:149], v[2:17]
	s_mul_i32 s52, s58, 0x200
	s_add_u32 s0, s44, s52
	s_addc_u32 s1, s45, 0
	s_add_u32 s2, s0, 0x8000
	s_addc_u32 s3, s1, 0
	s_mul_i32 s52, s59, 0x200
	s_add_u32 s4, s40, s52
	s_addc_u32 s5, s41, 0
	s_add_u32 s6, s4, 0x8000
	s_addc_u32 s7, s5, 0
	global_load_dwordx4 v[66:69], v213, s[0:1]
	global_load_dwordx4 v[70:73], v213, s[2:3]
	global_load_dwordx4 v[74:77], v217, s[4:5]
	global_load_dwordx4 v[78:81], v217, s[6:7]
	global_load_dwordx4 v[194:197], v221, s[10:11] offset:2048
	global_load_dwordx4 v[198:201], v221, s[10:11] offset:2064
	global_load_dwordx4 v[202:205], v221, s[10:11] offset:2112
	global_load_dwordx4 v[206:209], v221, s[10:11] offset:2128
	ds_read_b128 v[130:133], v219
	ds_read_b128 v[134:137], v220
	ds_read_b128 v[138:141], v219 offset:4608
	s_waitcnt lgkmcnt(11)
	v_mfma_f32_32x32x16_bf16 v[18:33], v[154:157], v[158:161], v[18:33]
	ds_read_b128 v[142:145], v219 offset:32
	ds_read_b128 v[146:149], v220 offset:32
	ds_read_b128 v[150:153], v219 offset:4640
	s_waitcnt lgkmcnt(13)
	v_mfma_f32_32x32x16_bf16 v[2:17], v[162:165], v[158:161], v[2:17]
	s_waitcnt lgkmcnt(11)
	v_mfma_f32_32x32x16_bf16 v[18:33], v[166:169], v[170:173], v[18:33]
	s_waitcnt lgkmcnt(10)
	v_mfma_f32_32x32x16_bf16 v[2:17], v[174:177], v[170:173], v[2:17]
	s_waitcnt lgkmcnt(0)
	s_barrier
; DI f32x16 mfma(bf16x8 a, bf16x8 b, f32x16 c) { return __builtin_amdgcn_mfma_f32_32x32x16_bf16(a, b, c, 0, 0, 0); }
; template <bool RFA, bool RFB, class LA, class LB, class EPI>
; DI void gemm_tile2s(u16* smem, int nk, LA la, LB lb, EPI epi) {
;     ...
;   auto ld = [&](u32x4 (&ra)[2], u32x4 (&rb)[2], int kt) __attribute__((always_inline)) {
;     const int k0 = kt * 64;
; #pragma unroll
;     for (int i = 0; i < 2; ++i) { const int c = tid + NTH * i; ra[i] = la(A_ROW(c), k0 + A_KC(c) * 8); rb[i] = lb(B_ROW(c), k0 + B_KC(c) * 8); }
;   };
;   auto stl = [&](u32x4 (&ra)[2], u32x4 (&rb)[2], int buf) __attribute__((always_inline)) {
; #pragma unroll
;     for (int i = 0; i < 2; ++i) {
;       const int c = tid + NTH * i;
;       *(u32x4*)(As + buf * TILE_ELEMS + A_ROW(c) * LDT + A_KC(c) * 8) = ra[i];
;       *(u32x4*)(Bs + buf * TILE_ELEMS + B_ROW(c) * LDT + B_KC(c) * 8) = rb[i];
;     }
;   };
;   auto compute = [&](int buf) __attribute__((always_inline)) {
;     const u16* Ab = As + buf * TILE_ELEMS + (wm * 64 + lr) * LDT + lh * 8;
;     const u16* Bb = Bs + buf * TILE_ELEMS + (wn * 32 + lr) * LDT + lh * 8;
; #pragma unroll
;     for (int ks = 0; ks < 4; ++ks) {
;       const bf16x8 a0 = *(const bf16x8*)(Ab + ks * 16);
;       const bf16x8 a1 = *(const bf16x8*)(Ab + 32 * LDT + ks * 16);
;       const bf16x8 b = *(const bf16x8*)(Bb + ks * 16);
;       acc[0] = mfma(a0, b, acc[0]);
;       acc[1] = mfma(a1, b, acc[1]);
;     }
;   };
;   ld(ra0, rb0, 0);
;   if (nk > 1) ld(ra1, rb1, 1);
;   stl(ra0, rb0, 0);
;   if (nk > 2) ld(ra0, rb0, 2);
;   __syncthreads();
; #pragma unroll 1
;   for (int kt = 0; kt < nk; kt += 2) {
;     compute(0);
;     if (kt + 1 < nk) { stl(ra1, rb1, 1); if (kt + 3 < nk) ld(ra1, rb1, kt + 3); }
;     __syncthreads();
;     if (kt + 1 < nk) {
;       compute(1);
;       if (kt + 2 < nk) { stl(ra0, rb0, 0); if (kt + 4 < nk) ld(ra0, rb0, kt + 4); }
;       __syncthreads();
	ds_read_b128 v[154:157], v219 offset:64
	ds_read_b128 v[158:161], v220 offset:64
	ds_read_b128 v[162:165], v219 offset:4672
	v_mfma_f32_32x32x16_bf16 v[18:33], v[130:133], v[134:137], v[18:33]
	ds_read_b128 v[166:169], v219 offset:96
	ds_read_b128 v[170:173], v220 offset:96
	ds_read_b128 v[174:177], v219 offset:4704
	v_mfma_f32_32x32x16_bf16 v[2:17], v[138:141], v[134:137], v[2:17]
	s_waitcnt vmcnt(20)
	ds_write_b128 v218, v[82:85] offset:36864
	ds_write_b128 v218, v[86:89] offset:46080
	v_mfma_f32_32x32x16_bf16 v[18:33], v[142:145], v[146:149], v[18:33]
	ds_write_b128 v223, v[90:93] offset:36864
	ds_write_b128 v223, v[94:97] offset:46080
	v_mfma_f32_32x32x16_bf16 v[2:17], v[150:153], v[146:149], v[2:17]
	global_load_dwordx4 v[82:85], v213, s[0:1] offset:128
	global_load_dwordx4 v[86:89], v213, s[2:3] offset:128
	global_load_dwordx4 v[90:93], v217, s[4:5] offset:128
	global_load_dwordx4 v[94:97], v217, s[6:7] offset:128
	ds_read_b128 v[130:133], v219 offset:18432
	ds_read_b128 v[134:137], v220 offset:18432
	ds_read_b128 v[138:141], v219 offset:23040
	s_waitcnt lgkmcnt(11)
	v_mfma_f32_32x32x16_bf16 v[18:33], v[154:157], v[158:161], v[18:33]
	ds_read_b128 v[142:145], v219 offset:18464
	ds_read_b128 v[146:149], v220 offset:18464
	ds_read_b128 v[150:153], v219 offset:23072
	s_waitcnt lgkmcnt(13)
	v_mfma_f32_32x32x16_bf16 v[2:17], v[162:165], v[158:161], v[2:17]
	s_waitcnt lgkmcnt(11)
	v_mfma_f32_32x32x16_bf16 v[18:33], v[166:169], v[170:173], v[18:33]
	s_waitcnt lgkmcnt(10)
	v_mfma_f32_32x32x16_bf16 v[2:17], v[174:177], v[170:173], v[2:17]
	s_waitcnt lgkmcnt(0)
	s_barrier
	ds_read_b128 v[154:157], v219 offset:18496
	ds_read_b128 v[158:161], v220 offset:18496
	ds_read_b128 v[162:165], v219 offset:23104
	v_mfma_f32_32x32x16_bf16 v[18:33], v[130:133], v[134:137], v[18:33]
	ds_read_b128 v[166:169], v219 offset:18528
	ds_read_b128 v[170:173], v220 offset:18528
	ds_read_b128 v[174:177], v219 offset:23136
	v_mfma_f32_32x32x16_bf16 v[2:17], v[138:141], v[134:137], v[2:17]
	s_waitcnt vmcnt(20)
	ds_write_b128 v218, v[98:101]
	ds_write_b128 v218, v[102:105] offset:9216
	v_mfma_f32_32x32x16_bf16 v[18:33], v[142:145], v[146:149], v[18:33]
	ds_write_b128 v223, v[106:109]
	ds_write_b128 v223, v[110:113] offset:9216
	v_mfma_f32_32x32x16_bf16 v[2:17], v[150:153], v[146:149], v[2:17]
	global_load_dwordx4 v[98:101], v213, s[0:1] offset:256
	global_load_dwordx4 v[102:105], v213, s[2:3] offset:256
	global_load_dwordx4 v[106:109], v217, s[4:5] offset:256
	global_load_dwordx4 v[110:113], v217, s[6:7] offset:256
	ds_read_b128 v[130:133], v219 offset:36864
	ds_read_b128 v[134:137], v220 offset:36864
	ds_read_b128 v[138:141], v219 offset:41472
	s_waitcnt lgkmcnt(11)
	v_mfma_f32_32x32x16_bf16 v[18:33], v[154:157], v[158:161], v[18:33]
	ds_read_b128 v[142:145], v219 offset:36896
	ds_read_b128 v[146:149], v220 offset:36896
	ds_read_b128 v[150:153], v219 offset:41504
	s_waitcnt lgkmcnt(13)
	v_mfma_f32_32x32x16_bf16 v[2:17], v[162:165], v[158:161], v[2:17]
	s_waitcnt lgkmcnt(11)
	v_mfma_f32_32x32x16_bf16 v[18:33], v[166:169], v[170:173], v[18:33]
	s_waitcnt lgkmcnt(10)
	v_mfma_f32_32x32x16_bf16 v[2:17], v[174:177], v[170:173], v[2:17]
	s_waitcnt lgkmcnt(0)
	s_barrier
	ds_read_b128 v[154:157], v219 offset:36928
	ds_read_b128 v[158:161], v220 offset:36928
	ds_read_b128 v[162:165], v219 offset:41536
	v_mfma_f32_32x32x16_bf16 v[18:33], v[130:133], v[134:137], v[18:33]
	ds_read_b128 v[166:169], v219 offset:36960
	ds_read_b128 v[170:173], v220 offset:36960
	ds_read_b128 v[174:177], v219 offset:41568
	v_mfma_f32_32x32x16_bf16 v[2:17], v[138:141], v[134:137], v[2:17]
	s_waitcnt vmcnt(16)
	ds_write_b128 v218, v[114:117] offset:18432
	ds_write_b128 v218, v[118:121] offset:27648
	v_mfma_f32_32x32x16_bf16 v[18:33], v[142:145], v[146:149], v[18:33]
	ds_write_b128 v223, v[122:125] offset:18432
	ds_write_b128 v223, v[126:129] offset:27648
	v_mfma_f32_32x32x16_bf16 v[2:17], v[150:153], v[146:149], v[2:17]
	global_load_dwordx4 v[114:117], v213, s[0:1] offset:384
	global_load_dwordx4 v[118:121], v213, s[2:3] offset:384
	global_load_dwordx4 v[122:125], v217, s[4:5] offset:384
	global_load_dwordx4 v[126:129], v217, s[6:7] offset:384
	ds_read_b128 v[130:133], v219
	ds_read_b128 v[134:137], v220
	ds_read_b128 v[138:141], v219 offset:4608
	s_waitcnt lgkmcnt(11)
	v_mfma_f32_32x32x16_bf16 v[18:33], v[154:157], v[158:161], v[18:33]
	ds_read_b128 v[142:145], v219 offset:32
	ds_read_b128 v[146:149], v220 offset:32
	ds_read_b128 v[150:153], v219 offset:4640
	s_waitcnt lgkmcnt(13)
	v_mfma_f32_32x32x16_bf16 v[2:17], v[162:165], v[158:161], v[2:17]
	s_waitcnt lgkmcnt(11)
	v_mfma_f32_32x32x16_bf16 v[18:33], v[166:169], v[170:173], v[18:33]
	s_waitcnt lgkmcnt(10)
	v_mfma_f32_32x32x16_bf16 v[2:17], v[174:177], v[170:173], v[2:17]
	s_waitcnt lgkmcnt(0)
	s_barrier
; DI f32x16 mfma(bf16x8 a, bf16x8 b, f32x16 c) { return __builtin_amdgcn_mfma_f32_32x32x16_bf16(a, b, c, 0, 0, 0); }
; #define TASK_LOOP(t, nt, base) for (int t = (int)((blockIdx.x + gridDim.x - ((unsigned)(base) % gridDim.x)) % gridDim.x); t < (nt); t += gridDim.x)
; template <bool RFA, bool RFB, class LA, class LB, class EPI>
; DI void gemm_tile2s(u16* smem, int nk, LA la, LB lb, EPI epi) {
;     ...
;   auto ld = [&](u32x4 (&ra)[2], u32x4 (&rb)[2], int kt) __attribute__((always_inline)) {
;     const int k0 = kt * 64;
; #pragma unroll
;     for (int i = 0; i < 2; ++i) { const int c = tid + NTH * i; ra[i] = la(A_ROW(c), k0 + A_KC(c) * 8); rb[i] = lb(B_ROW(c), k0 + B_KC(c) * 8); }
;   };
;   auto stl = [&](u32x4 (&ra)[2], u32x4 (&rb)[2], int buf) __attribute__((always_inline)) {
; #pragma unroll
;     for (int i = 0; i < 2; ++i) {
;       const int c = tid + NTH * i;
;       *(u32x4*)(As + buf * TILE_ELEMS + A_ROW(c) * LDT + A_KC(c) * 8) = ra[i];
;       *(u32x4*)(Bs + buf * TILE_ELEMS + B_ROW(c) * LDT + B_KC(c) * 8) = rb[i];
;     }
;   };
;   auto compute = [&](int buf) __attribute__((always_inline)) {
;     const u16* Ab = As + buf * TILE_ELEMS + (wm * 64 + lr) * LDT + lh * 8;
;     const u16* Bb = Bs + buf * TILE_ELEMS + (wn * 32 + lr) * LDT + lh * 8;
; #pragma unroll
;     for (int ks = 0; ks < 4; ++ks) {
;       const bf16x8 a0 = *(const bf16x8*)(Ab + ks * 16);
;       const bf16x8 a1 = *(const bf16x8*)(Ab + 32 * LDT + ks * 16);
;       const bf16x8 b = *(const bf16x8*)(Bb + ks * 16);
;       acc[0] = mfma(a0, b, acc[0]);
;       acc[1] = mfma(a1, b, acc[1]);
;     }
;   };
;   ld(ra0, rb0, 0);
;   if (nk > 1) ld(ra1, rb1, 1);
;   stl(ra0, rb0, 0);
;   if (nk > 2) ld(ra0, rb0, 2);
;   __syncthreads();
; #pragma unroll 1
;   for (int kt = 0; kt < nk; kt += 2) {
;     compute(0);
;     if (kt + 1 < nk) { stl(ra1, rb1, 1); if (kt + 3 < nk) ld(ra1, rb1, kt + 3); }
;     __syncthreads();
;     if (kt + 1 < nk) {
;       compute(1);
;       if (kt + 2 < nk) { stl(ra0, rb0, 0); if (kt + 4 < nk) ld(ra0, rb0, kt + 4); }
;       __syncthreads();
; DI void phase_merge(const Prm& p, u16* smem, int l, int& base) {
;   TASK_LOOP(t, 8 * 128, base) {
;     const int tn = t & 7, tm = t >> 3, n0 = tn * 128, m0 = tm * 128;
	ds_read_b128 v[154:157], v219 offset:64
	ds_read_b128 v[158:161], v220 offset:64
	ds_read_b128 v[162:165], v219 offset:4672
	v_mfma_f32_32x32x16_bf16 v[18:33], v[130:133], v[134:137], v[18:33]
	ds_read_b128 v[166:169], v219 offset:96
	ds_read_b128 v[170:173], v220 offset:96
	ds_read_b128 v[174:177], v219 offset:4704
	v_mfma_f32_32x32x16_bf16 v[2:17], v[138:141], v[134:137], v[2:17]
	s_waitcnt vmcnt(16)
	ds_write_b128 v218, v[66:69] offset:36864
	ds_write_b128 v218, v[70:73] offset:46080
	v_mfma_f32_32x32x16_bf16 v[18:33], v[142:145], v[146:149], v[18:33]
	ds_write_b128 v223, v[74:77] offset:36864
	ds_write_b128 v223, v[78:81] offset:46080
	v_mfma_f32_32x32x16_bf16 v[2:17], v[150:153], v[146:149], v[2:17]
	s_add_i32 s50, s31, s30
	s_cmpk_lt_i32 s50, 0x400
	s_cselect_b32 s50, s50, s31
	s_and_b32 s52, s50, 7
	s_lshl_b32 s52, s52, 7
	s_lshr_b32 s53, s50, 8
	s_lshl_b32 s53, s53, 5
	s_or_b32 s52, s52, s53
	s_bfe_u32 s53, s50, 0x50003
	s_or_b32 s52, s52, s53
	s_and_b32 s60, s52, 7
	s_lshl_b32 s60, s60, 7
	s_lshr_b32 s61, s52, 3
	s_lshl_b32 s61, s61, 7
	s_mul_i32 s52, s60, 0x600
	s_add_u32 s0, s16, s52
	s_addc_u32 s1, s17, 0
	s_add_u32 s2, s0, 0x18000
	s_addc_u32 s3, s1, 0
	s_mul_i32 s52, s61, 0x600
	s_add_u32 s4, s14, s52
	s_addc_u32 s5, s15, 0
	s_add_u32 s6, s4, 0x18000
	s_addc_u32 s7, s5, 0
	global_load_dwordx4 v[66:69], v210, s[0:1]
	global_load_dwordx4 v[70:73], v210, s[2:3]
	global_load_dwordx4 v[74:77], v214, s[4:5]
	global_load_dwordx4 v[78:81], v214, s[6:7]
	ds_read_b128 v[130:133], v219 offset:18432
	ds_read_b128 v[134:137], v220 offset:18432
	ds_read_b128 v[138:141], v219 offset:23040
	s_waitcnt lgkmcnt(11)
	v_mfma_f32_32x32x16_bf16 v[18:33], v[154:157], v[158:161], v[18:33]
	ds_read_b128 v[142:145], v219 offset:18464
	ds_read_b128 v[146:149], v220 offset:18464
	ds_read_b128 v[150:153], v219 offset:23072
	s_waitcnt lgkmcnt(13)
	v_mfma_f32_32x32x16_bf16 v[2:17], v[162:165], v[158:161], v[2:17]
	s_waitcnt lgkmcnt(11)
	v_mfma_f32_32x32x16_bf16 v[18:33], v[166:169], v[170:173], v[18:33]
	s_waitcnt lgkmcnt(10)
	v_mfma_f32_32x32x16_bf16 v[2:17], v[174:177], v[170:173], v[2:17]
	s_waitcnt lgkmcnt(0)
	s_barrier
	ds_read_b128 v[154:157], v219 offset:18496
	ds_read_b128 v[158:161], v220 offset:18496
	ds_read_b128 v[162:165], v219 offset:23104
	v_mfma_f32_32x32x16_bf16 v[18:33], v[130:133], v[134:137], v[18:33]
	ds_read_b128 v[166:169], v219 offset:18528
	ds_read_b128 v[170:173], v220 offset:18528
	ds_read_b128 v[174:177], v219 offset:23136
	v_mfma_f32_32x32x16_bf16 v[2:17], v[138:141], v[134:137], v[2:17]
	s_waitcnt vmcnt(12)
	ds_write_b128 v218, v[82:85]
	ds_write_b128 v218, v[86:89] offset:9216
	v_mfma_f32_32x32x16_bf16 v[18:33], v[142:145], v[146:149], v[18:33]
	ds_write_b128 v223, v[90:93]
	ds_write_b128 v223, v[94:97] offset:9216
	v_mfma_f32_32x32x16_bf16 v[2:17], v[150:153], v[146:149], v[2:17]
	global_load_dwordx4 v[82:85], v210, s[0:1] offset:128
	global_load_dwordx4 v[86:89], v210, s[2:3] offset:128
	global_load_dwordx4 v[90:93], v214, s[4:5] offset:128
	global_load_dwordx4 v[94:97], v214, s[6:7] offset:128
	ds_read_b128 v[130:133], v219 offset:36864
	ds_read_b128 v[134:137], v220 offset:36864
	ds_read_b128 v[138:141], v219 offset:41472
	s_waitcnt lgkmcnt(11)
	v_mfma_f32_32x32x16_bf16 v[18:33], v[154:157], v[158:161], v[18:33]
	ds_read_b128 v[142:145], v219 offset:36896
	ds_read_b128 v[146:149], v220 offset:36896
	ds_read_b128 v[150:153], v219 offset:41504
	s_waitcnt lgkmcnt(13)
	v_mfma_f32_32x32x16_bf16 v[2:17], v[162:165], v[158:161], v[2:17]
	s_waitcnt lgkmcnt(11)
	v_mfma_f32_32x32x16_bf16 v[18:33], v[166:169], v[170:173], v[18:33]
	s_waitcnt lgkmcnt(10)
	v_mfma_f32_32x32x16_bf16 v[2:17], v[174:177], v[170:173], v[2:17]
	s_waitcnt vmcnt(32)
	s_nop 15
	v_lshlrev_b32_e32 v226, 16, v178
	v_and_b32_e32 v227, 0xffff0000, v178
	v_pk_fma_f32 v[34:35], v[226:227], v[18:19], v[34:35]
	v_lshlrev_b32_e32 v228, 16, v179
	v_and_b32_e32 v229, 0xffff0000, v179
	v_pk_fma_f32 v[36:37], v[228:229], v[20:21], v[36:37]
	v_lshlrev_b32_e32 v234, 16, v180
	v_and_b32_e32 v235, 0xffff0000, v180
	v_pk_fma_f32 v[38:39], v[234:235], v[22:23], v[38:39]
	v_lshlrev_b32_e32 v236, 16, v181
	v_and_b32_e32 v237, 0xffff0000, v181
	v_pk_fma_f32 v[40:41], v[236:237], v[24:25], v[40:41]
	v_lshlrev_b32_e32 v226, 16, v182
	v_and_b32_e32 v227, 0xffff0000, v182
	v_pk_fma_f32 v[42:43], v[226:227], v[26:27], v[42:43]
	v_lshlrev_b32_e32 v228, 16, v183
	v_and_b32_e32 v229, 0xffff0000, v183
	v_pk_fma_f32 v[44:45], v[228:229], v[28:29], v[44:45]
	v_lshlrev_b32_e32 v234, 16, v184
	v_and_b32_e32 v235, 0xffff0000, v184
	v_pk_fma_f32 v[46:47], v[234:235], v[30:31], v[46:47]
	v_lshlrev_b32_e32 v236, 16, v185
	v_and_b32_e32 v237, 0xffff0000, v185
	v_pk_fma_f32 v[48:49], v[236:237], v[32:33], v[48:49]
	v_lshlrev_b32_e32 v226, 16, v186
	v_and_b32_e32 v227, 0xffff0000, v186
	v_pk_fma_f32 v[50:51], v[226:227], v[2:3], v[50:51]
	v_lshlrev_b32_e32 v228, 16, v187
	v_and_b32_e32 v229, 0xffff0000, v187
	v_pk_fma_f32 v[52:53], v[228:229], v[4:5], v[52:53]
	v_lshlrev_b32_e32 v234, 16, v188
	v_and_b32_e32 v235, 0xffff0000, v188
	v_pk_fma_f32 v[54:55], v[234:235], v[6:7], v[54:55]
	v_lshlrev_b32_e32 v236, 16, v189
	v_and_b32_e32 v237, 0xffff0000, v189
	v_pk_fma_f32 v[56:57], v[236:237], v[8:9], v[56:57]
	v_lshlrev_b32_e32 v226, 16, v190
	v_and_b32_e32 v227, 0xffff0000, v190
	v_pk_fma_f32 v[58:59], v[226:227], v[10:11], v[58:59]
	v_lshlrev_b32_e32 v228, 16, v191
	v_and_b32_e32 v229, 0xffff0000, v191
	v_pk_fma_f32 v[60:61], v[228:229], v[12:13], v[60:61]
	v_lshlrev_b32_e32 v234, 16, v192
	v_and_b32_e32 v235, 0xffff0000, v192
	v_pk_fma_f32 v[62:63], v[234:235], v[14:15], v[62:63]
	v_lshlrev_b32_e32 v236, 16, v193
	v_and_b32_e32 v237, 0xffff0000, v193
	v_pk_fma_f32 v[64:65], v[236:237], v[16:17], v[64:65]
	s_waitcnt lgkmcnt(0)
	s_barrier
; DI f32x16 mfma(bf16x8 a, bf16x8 b, f32x16 c) { return __builtin_amdgcn_mfma_f32_32x32x16_bf16(a, b, c, 0, 0, 0); }
; template <bool RFA, bool RFB, class LA, class LB, class EPI>
; DI void gemm_tile2s(u16* smem, int nk, LA la, LB lb, EPI epi) {
;     ...
;   auto ld = [&](u32x4 (&ra)[2], u32x4 (&rb)[2], int kt) __attribute__((always_inline)) {
;     const int k0 = kt * 64;
; #pragma unroll
;     for (int i = 0; i < 2; ++i) { const int c = tid + NTH * i; ra[i] = la(A_ROW(c), k0 + A_KC(c) * 8); rb[i] = lb(B_ROW(c), k0 + B_KC(c) * 8); }
;   };
;   auto stl = [&](u32x4 (&ra)[2], u32x4 (&rb)[2], int buf) __attribute__((always_inline)) {
; #pragma unroll
;     for (int i = 0; i < 2; ++i) {
;       const int c = tid + NTH * i;
;       *(u32x4*)(As + buf * TILE_ELEMS + A_ROW(c) * LDT + A_KC(c) * 8) = ra[i];
;       *(u32x4*)(Bs + buf * TILE_ELEMS + B_ROW(c) * LDT + B_KC(c) * 8) = rb[i];
;     }
;   };
;   auto compute = [&](int buf) __attribute__((always_inline)) {
;     const u16* Ab = As + buf * TILE_ELEMS + (wm * 64 + lr) * LDT + lh * 8;
;     const u16* Bb = Bs + buf * TILE_ELEMS + (wn * 32 + lr) * LDT + lh * 8;
; #pragma unroll
;     for (int ks = 0; ks < 4; ++ks) {
;       const bf16x8 a0 = *(const bf16x8*)(Ab + ks * 16);
;       const bf16x8 a1 = *(const bf16x8*)(Ab + 32 * LDT + ks * 16);
;       const bf16x8 b = *(const bf16x8*)(Bb + ks * 16);
;       acc[0] = mfma(a0, b, acc[0]);
;       acc[1] = mfma(a1, b, acc[1]);
;     }
;   };
;   ld(ra0, rb0, 0);
;   if (nk > 1) ld(ra1, rb1, 1);
;   stl(ra0, rb0, 0);
;   if (nk > 2) ld(ra0, rb0, 2);
;   __syncthreads();
; #pragma unroll 1
;   for (int kt = 0; kt < nk; kt += 2) {
;     compute(0);
;     if (kt + 1 < nk) { stl(ra1, rb1, 1); if (kt + 3 < nk) ld(ra1, rb1, kt + 3); }
;     __syncthreads();
;     if (kt + 1 < nk) {
;       compute(1);
;       if (kt + 2 < nk) { stl(ra0, rb0, 0); if (kt + 4 < nk) ld(ra0, rb0, kt + 4); }
;       __syncthreads();
	ds_read_b128 v[154:157], v219 offset:36928
	ds_read_b128 v[158:161], v220 offset:36928
	ds_read_b128 v[162:165], v219 offset:41536
	v_mfma_f32_32x32x16_bf16 v[18:33], v[130:133], v[134:137], 0
	ds_read_b128 v[166:169], v219 offset:36960
	ds_read_b128 v[170:173], v220 offset:36960
	ds_read_b128 v[174:177], v219 offset:41568
	v_mfma_f32_32x32x16_bf16 v[2:17], v[138:141], v[134:137], 0
	s_waitcnt vmcnt(12)
	ds_write_b128 v218, v[98:101] offset:18432
	ds_write_b128 v218, v[102:105] offset:27648
	v_mfma_f32_32x32x16_bf16 v[18:33], v[142:145], v[146:149], v[18:33]
	ds_write_b128 v223, v[106:109] offset:18432
	ds_write_b128 v223, v[110:113] offset:27648
	v_mfma_f32_32x32x16_bf16 v[2:17], v[150:153], v[146:149], v[2:17]
	global_load_dwordx4 v[98:101], v210, s[0:1] offset:256
	global_load_dwordx4 v[102:105], v210, s[2:3] offset:256
	global_load_dwordx4 v[106:109], v214, s[4:5] offset:256
	global_load_dwordx4 v[110:113], v214, s[6:7] offset:256
	ds_read_b128 v[130:133], v219
	ds_read_b128 v[134:137], v220
	ds_read_b128 v[138:141], v219 offset:4608
	s_waitcnt lgkmcnt(11)
	v_mfma_f32_32x32x16_bf16 v[18:33], v[154:157], v[158:161], v[18:33]
	ds_read_b128 v[142:145], v219 offset:32
	ds_read_b128 v[146:149], v220 offset:32
	ds_read_b128 v[150:153], v219 offset:4640
	s_waitcnt lgkmcnt(13)
	v_mfma_f32_32x32x16_bf16 v[2:17], v[162:165], v[158:161], v[2:17]
	s_waitcnt lgkmcnt(11)
	v_mfma_f32_32x32x16_bf16 v[18:33], v[166:169], v[170:173], v[18:33]
	s_waitcnt lgkmcnt(10)
	v_mfma_f32_32x32x16_bf16 v[2:17], v[174:177], v[170:173], v[2:17]
	s_waitcnt lgkmcnt(0)
	s_barrier
	ds_read_b128 v[154:157], v219 offset:64
	ds_read_b128 v[158:161], v220 offset:64
	ds_read_b128 v[162:165], v219 offset:4672
	v_mfma_f32_32x32x16_bf16 v[18:33], v[130:133], v[134:137], v[18:33]
	ds_read_b128 v[166:169], v219 offset:96
	ds_read_b128 v[170:173], v220 offset:96
	ds_read_b128 v[174:177], v219 offset:4704
	v_mfma_f32_32x32x16_bf16 v[2:17], v[138:141], v[134:137], v[2:17]
	s_waitcnt vmcnt(12)
	ds_write_b128 v218, v[114:117] offset:36864
	ds_write_b128 v218, v[118:121] offset:46080
	v_mfma_f32_32x32x16_bf16 v[18:33], v[142:145], v[146:149], v[18:33]
	ds_write_b128 v223, v[122:125] offset:36864
	ds_write_b128 v223, v[126:129] offset:46080
	v_mfma_f32_32x32x16_bf16 v[2:17], v[150:153], v[146:149], v[2:17]
	global_load_dwordx4 v[114:117], v210, s[0:1] offset:384
	global_load_dwordx4 v[118:121], v210, s[2:3] offset:384
	global_load_dwordx4 v[122:125], v214, s[4:5] offset:384
	global_load_dwordx4 v[126:129], v214, s[6:7] offset:384
	ds_read_b128 v[130:133], v219 offset:18432
	ds_read_b128 v[134:137], v220 offset:18432
	ds_read_b128 v[138:141], v219 offset:23040
	s_waitcnt lgkmcnt(11)
	v_mfma_f32_32x32x16_bf16 v[18:33], v[154:157], v[158:161], v[18:33]
	ds_read_b128 v[142:145], v219 offset:18464
	ds_read_b128 v[146:149], v220 offset:18464
	ds_read_b128 v[150:153], v219 offset:23072
	s_waitcnt lgkmcnt(13)
	v_mfma_f32_32x32x16_bf16 v[2:17], v[162:165], v[158:161], v[2:17]
	s_waitcnt lgkmcnt(11)
	v_mfma_f32_32x32x16_bf16 v[18:33], v[166:169], v[170:173], v[18:33]
	s_waitcnt lgkmcnt(10)
	v_mfma_f32_32x32x16_bf16 v[2:17], v[174:177], v[170:173], v[2:17]
	s_waitcnt lgkmcnt(0)
	s_barrier
	ds_read_b128 v[154:157], v219 offset:18496
	ds_read_b128 v[158:161], v220 offset:18496
	ds_read_b128 v[162:165], v219 offset:23104
	v_mfma_f32_32x32x16_bf16 v[18:33], v[130:133], v[134:137], v[18:33]
	ds_read_b128 v[166:169], v219 offset:18528
	ds_read_b128 v[170:173], v220 offset:18528
	ds_read_b128 v[174:177], v219 offset:23136
	v_mfma_f32_32x32x16_bf16 v[2:17], v[138:141], v[134:137], v[2:17]
	s_waitcnt vmcnt(12)
	ds_write_b128 v218, v[66:69]
	ds_write_b128 v218, v[70:73] offset:9216
	v_mfma_f32_32x32x16_bf16 v[18:33], v[142:145], v[146:149], v[18:33]
	ds_write_b128 v223, v[74:77]
	ds_write_b128 v223, v[78:81] offset:9216
	v_mfma_f32_32x32x16_bf16 v[2:17], v[150:153], v[146:149], v[2:17]
	global_load_dwordx4 v[66:69], v210, s[0:1] offset:512
	global_load_dwordx4 v[70:73], v210, s[2:3] offset:512
	global_load_dwordx4 v[74:77], v214, s[4:5] offset:512
	global_load_dwordx4 v[78:81], v214, s[6:7] offset:512
	ds_read_b128 v[130:133], v219 offset:36864
	ds_read_b128 v[134:137], v220 offset:36864
	ds_read_b128 v[138:141], v219 offset:41472
	s_waitcnt lgkmcnt(11)
	v_mfma_f32_32x32x16_bf16 v[18:33], v[154:157], v[158:161], v[18:33]
	ds_read_b128 v[142:145], v219 offset:36896
	ds_read_b128 v[146:149], v220 offset:36896
	ds_read_b128 v[150:153], v219 offset:41504
	s_waitcnt lgkmcnt(13)
	v_mfma_f32_32x32x16_bf16 v[2:17], v[162:165], v[158:161], v[2:17]
	s_waitcnt lgkmcnt(11)
	v_mfma_f32_32x32x16_bf16 v[18:33], v[166:169], v[170:173], v[18:33]
	s_waitcnt lgkmcnt(10)
	v_mfma_f32_32x32x16_bf16 v[2:17], v[174:177], v[170:173], v[2:17]
	s_waitcnt lgkmcnt(0)
	s_barrier
; DI float bflo(unsigned w) { return __uint_as_float(w << 16); }
; DI float bfhi(unsigned w) { return __uint_as_float(w & 0xffff0000u); }
; template <class ACC>
; DI void merge_branch(const Prm& p, u16* smem, const u16* W, const u16* X, int ld, int bi, int n0, int m0, ACC& macc) {
;   auto la = [&](int row, int k) __attribute__((always_inline)) { return *(const u32x4*)(W + (size_t)(n0 + (row & ~31) + perm_m(row & 31)) * ld + k); };
;   auto lb = [&](int row, int k) __attribute__((always_inline)) { return *(const u32x4*)(X + (size_t)(m0 + row) * ld + k); };
;   auto epi = [&](f32x16 (&acc)[2], int wm, int wn, int lane) __attribute__((always_inline)) {
;     const int lr = lane & 31, lh = lane >> 5;
;     const int tok = m0 + wn * 32 + lr;
; #pragma unroll
;     for (int i = 0; i < 2; ++i)
; #pragma unroll
;       for (int h2 = 0; h2 < 2; ++h2) {
;         const int n = n0 + wm * 64 + i * 32 + 16 * lh + 8 * h2;
;         const u32x4 gz = *(const u32x4*)(p.zg + (size_t)tok * 4096 + bi * 1024 + n);
; #pragma unroll
;         for (int e = 0; e < 4; ++e) {
;           macc[i][8 * h2 + 2 * e] += bflo(gz[e]) * acc[i][8 * h2 + 2 * e];
;           macc[i][8 * h2 + 2 * e + 1] += bfhi(gz[e]) * acc[i][8 * h2 + 2 * e + 1];
;         }
;       }
;   };
;   gemm_tile2s<false, false>(smem, ld >> 6, la, lb, epi);
; }
; DI void phase_merge(const Prm& p, u16* smem, int l, int& base) {
;   TASK_LOOP(t, 8 * 128, base) {
;     const int tn = t & 7, tm = t >> 3, n0 = tn * 128, m0 = tm * 128;
;     f32x16 macc[2];
;     macc[0] = zero16(); macc[1] = zero16();
;     merge_branch(p, smem, p.PaT + (size_t)l * 1024 * 768, p.UT, 768, 0, n0, m0, macc);
;     merge_branch(p, smem, p.PbT + (size_t)l * 1024 * 128, p.ob, 128, 1, n0, m0, macc);
;     ...
;     merge_branch(p, smem, p.PdT + (size_t)l * 1024 * 256, p.od, 256, 3, n0, m0, macc);
;     const int tid2 = tidx(), lane = tid2 & 63, wave = tid2 >> 6, wm = wave >> 2, wn = wave & 3, lr = lane & 31, lh = lane >> 5;
;     const int tok = m0 + wn * 32 + lr;
; #pragma unroll
;     for (int i = 0; i < 2; ++i)
; #pragma unroll
;       for (int h2 = 0; h2 < 2; ++h2) {
;         u32x4 o;
; #pragma unroll
;         for (int e = 0; e < 4; ++e) o[e] = pack2(macc[i][8 * h2 + 2 * e], macc[i][8 * h2 + 2 * e + 1]);
;         *(u32x4*)(p.hbuf + (size_t)tok * 1024 + n0 + wm * 64 + i * 32 + 16 * lh + 8 * h2) = o;
;       }
;   }
;   base += 8 * 128;
; }
	ds_read_b128 v[154:157], v219 offset:36928
	ds_read_b128 v[158:161], v220 offset:36928
	ds_read_b128 v[162:165], v219 offset:41536
	v_mfma_f32_32x32x16_bf16 v[18:33], v[130:133], v[134:137], v[18:33]
	ds_read_b128 v[166:169], v219 offset:36960
	ds_read_b128 v[170:173], v220 offset:36960
	ds_read_b128 v[174:177], v219 offset:41568
	v_mfma_f32_32x32x16_bf16 v[2:17], v[138:141], v[134:137], v[2:17]
	s_waitcnt vmcnt(12)
	ds_write_b128 v218, v[82:85] offset:18432
	ds_write_b128 v218, v[86:89] offset:27648
	v_mfma_f32_32x32x16_bf16 v[18:33], v[142:145], v[146:149], v[18:33]
	ds_write_b128 v223, v[90:93] offset:18432
	ds_write_b128 v223, v[94:97] offset:27648
	v_mfma_f32_32x32x16_bf16 v[2:17], v[150:153], v[146:149], v[2:17]
	global_load_dwordx4 v[82:85], v210, s[0:1] offset:640
	global_load_dwordx4 v[86:89], v210, s[2:3] offset:640
	global_load_dwordx4 v[90:93], v214, s[4:5] offset:640
	global_load_dwordx4 v[94:97], v214, s[6:7] offset:640
	ds_read_b128 v[130:133], v219
	ds_read_b128 v[134:137], v220
	ds_read_b128 v[138:141], v219 offset:4608
	s_waitcnt lgkmcnt(11)
	v_mfma_f32_32x32x16_bf16 v[18:33], v[154:157], v[158:161], v[18:33]
	ds_read_b128 v[142:145], v219 offset:32
	ds_read_b128 v[146:149], v220 offset:32
	ds_read_b128 v[150:153], v219 offset:4640
	s_waitcnt lgkmcnt(13)
	v_mfma_f32_32x32x16_bf16 v[2:17], v[162:165], v[158:161], v[2:17]
	s_waitcnt lgkmcnt(11)
	v_mfma_f32_32x32x16_bf16 v[18:33], v[166:169], v[170:173], v[18:33]
	s_waitcnt lgkmcnt(10)
	v_mfma_f32_32x32x16_bf16 v[2:17], v[174:177], v[170:173], v[2:17]
	s_waitcnt vmcnt(36)
	s_nop 15
	v_lshlrev_b32_e32 v226, 16, v194
	v_and_b32_e32 v227, 0xffff0000, v194
	v_pk_fma_f32 v[34:35], v[226:227], v[18:19], v[34:35]
	v_lshlrev_b32_e32 v228, 16, v195
	v_and_b32_e32 v229, 0xffff0000, v195
	v_pk_fma_f32 v[36:37], v[228:229], v[20:21], v[36:37]
	v_lshlrev_b32_e32 v234, 16, v196
	v_and_b32_e32 v235, 0xffff0000, v196
	v_pk_fma_f32 v[38:39], v[234:235], v[22:23], v[38:39]
	v_lshlrev_b32_e32 v236, 16, v197
	v_and_b32_e32 v237, 0xffff0000, v197
	v_pk_fma_f32 v[40:41], v[236:237], v[24:25], v[40:41]
	v_lshlrev_b32_e32 v226, 16, v198
	v_and_b32_e32 v227, 0xffff0000, v198
	v_pk_fma_f32 v[42:43], v[226:227], v[26:27], v[42:43]
	v_lshlrev_b32_e32 v228, 16, v199
	v_and_b32_e32 v229, 0xffff0000, v199
	v_pk_fma_f32 v[44:45], v[228:229], v[28:29], v[44:45]
	v_lshlrev_b32_e32 v234, 16, v200
	v_and_b32_e32 v235, 0xffff0000, v200
	v_pk_fma_f32 v[46:47], v[234:235], v[30:31], v[46:47]
	v_lshlrev_b32_e32 v236, 16, v201
	v_and_b32_e32 v237, 0xffff0000, v201
	v_pk_fma_f32 v[48:49], v[236:237], v[32:33], v[48:49]
	v_lshlrev_b32_e32 v226, 16, v202
	v_and_b32_e32 v227, 0xffff0000, v202
	v_pk_fma_f32 v[50:51], v[226:227], v[2:3], v[50:51]
	v_lshlrev_b32_e32 v228, 16, v203
	v_and_b32_e32 v229, 0xffff0000, v203
	v_pk_fma_f32 v[52:53], v[228:229], v[4:5], v[52:53]
	v_lshlrev_b32_e32 v234, 16, v204
	v_and_b32_e32 v235, 0xffff0000, v204
	v_pk_fma_f32 v[54:55], v[234:235], v[6:7], v[54:55]
	v_lshlrev_b32_e32 v236, 16, v205
	v_and_b32_e32 v237, 0xffff0000, v205
	v_pk_fma_f32 v[56:57], v[236:237], v[8:9], v[56:57]
	v_lshlrev_b32_e32 v226, 16, v206
	v_and_b32_e32 v227, 0xffff0000, v206
	v_pk_fma_f32 v[58:59], v[226:227], v[10:11], v[58:59]
	v_lshlrev_b32_e32 v228, 16, v207
	v_and_b32_e32 v229, 0xffff0000, v207
	v_pk_fma_f32 v[60:61], v[228:229], v[12:13], v[60:61]
	v_lshlrev_b32_e32 v234, 16, v208
	v_and_b32_e32 v235, 0xffff0000, v208
	v_pk_fma_f32 v[62:63], v[234:235], v[14:15], v[62:63]
	v_lshlrev_b32_e32 v236, 16, v209
	v_and_b32_e32 v237, 0xffff0000, v209
	v_pk_fma_f32 v[64:65], v[236:237], v[16:17], v[64:65]
	v_cvt_pk_bf16_f32 v178, v34, v35
	v_cvt_pk_bf16_f32 v179, v36, v37
	v_cvt_pk_bf16_f32 v180, v38, v39
	v_cvt_pk_bf16_f32 v181, v40, v41
	v_cvt_pk_bf16_f32 v182, v42, v43
	v_cvt_pk_bf16_f32 v183, v44, v45
	v_cvt_pk_bf16_f32 v184, v46, v47
	v_cvt_pk_bf16_f32 v185, v48, v49
	v_cvt_pk_bf16_f32 v186, v50, v51
	v_cvt_pk_bf16_f32 v187, v52, v53
	v_cvt_pk_bf16_f32 v188, v54, v55
	v_cvt_pk_bf16_f32 v189, v56, v57
	v_cvt_pk_bf16_f32 v190, v58, v59
	v_cvt_pk_bf16_f32 v191, v60, v61
	v_cvt_pk_bf16_f32 v192, v62, v63
	v_cvt_pk_bf16_f32 v193, v64, v65
	global_store_dwordx4 v222, v[178:181], s[12:13]
	global_store_dwordx4 v222, v[182:185], s[12:13] offset:16
	global_store_dwordx4 v222, v[186:189], s[12:13] offset:64
	global_store_dwordx4 v222, v[190:193], s[12:13] offset:80
	s_waitcnt lgkmcnt(0)
	s_barrier
	s_add_i32 s31, s31, s30
	s_mov_b32 s58, s60
	s_mov_b32 s59, s61
	s_cmpk_lt_i32 s31, 0x400
	s_cbranch_scc1 .Lmrg_task
